# 4+4 LDS-DMA per load segment with all LDS fragment reads issued before the DMA loads in every segment
# speedup vs baseline: 1.0053x; 1.0053x over previous
; #define PG8_STAGE(bufoff, gbase, voff) do { _Pragma("unroll") for (int _i = 0; _i < 2; ++_i) \
;         __builtin_amdgcn_global_load_lds((const unsigned*)((const char*)(gbase) + (voff)[_i]), (LAS unsigned*)(lds + (bufoff) + ldsw + _i * 8192), 16, 0, 0); } while (0)
; #define PG8_LDA(dst, b, h) do { _Pragma("unroll") for (int m = 0; m < 4; ++m) _Pragma("unroll") for (int k = 0; k < 2; ++k) dst[m][k] = *(const LAS bf16x8*)(lds + PG8_SA(b, h) + aoff + m * 2048 + k * 1024); } while (0)
; #define PG8_LDB(dst, b, h) do { _Pragma("unroll") for (int n = 0; n < 2; ++n) _Pragma("unroll") for (int k = 0; k < 2; ++k) dst[n][k] = *(const LAS bf16x8*)(lds + PG8_SB(b, h) + boff + n * 2048 + k * 1024); } while (0)
; #define PG8_MMA(ai, bj, At, Bt) do { __builtin_amdgcn_s_setprio(1); _Pragma("unroll") for (int m = 0; m < 4; ++m) _Pragma("unroll") for (int n = 0; n < 2; ++n) _Pragma("unroll") for (int k = 0; k < 2; ++k) \
;         acc[ai][bj][m][n] = __builtin_amdgcn_mfma_f32_16x16x32_bf16(Bt[n][k], At[m][k], acc[ai][bj][m][n], 0, 0, 0); __builtin_amdgcn_s_setprio(0); } while (0)
; #define PG8_WAIT_V(n) asm volatile("s_waitcnt vmcnt(" #n ")" ::: "memory")
; #define PG8_WAIT_L(n) asm volatile("s_waitcnt lgkmcnt(" #n ")" ::: "memory")
; #define PG8_BAR __builtin_amdgcn_s_barrier()
; #define PG8_SCHED __builtin_amdgcn_sched_barrier(0)
; template <class Epi, class Sched, bool ALIGN_EPI = false, bool SP2 = false>
; __device__ __forceinline__ void gemm_phase(LAS unsigned char* lds, const Gemm g, const Sched& S, const Epi& E) {
;     ...
;             const char* a1 = cA + (size_t)(t + 1) * kstep;
;             const char* a2 = last ? nA : cA + (size_t)(t + 2) * kstep; const char* b2 = last ? nB : cB + (size_t)(t + 2) * kstep;
;             const char* a3 = a2 + kstep; const char* b3 = b2 + kstep;
;             if (last && has_next) S.a_ready(nxt);
;             if constexpr (SP2) {
;             PG8_LDB(B0, 0, 0); PG8_LDB(B1, 0, 1); PG8_SCHED; PG8_LDA(At, 0, 0); PG8_STAGE(PG8_SA(1, 1), a1 + hstep, voffA);
;             PG8_WAIT_V(8); PG8_WAIT_L(0); PG8_BAR; PG8_MMA(0, 0, At, B0); PG8_MMA(0, 1, At, B1); PG8_BAR; PG8_SCHED;
;             PG8_LDA(At, 0, 1); PG8_STAGE(PG8_SB(0, 0), b2, voffB); PG8_STAGE(PG8_SB(0, 1), b2 + hstep, voffB); PG8_STAGE(PG8_SA(0, 0), a2, voffA);
;             PG8_WAIT_V(8); PG8_WAIT_L(0); PG8_BAR; PG8_MMA(1, 0, At, B0); PG8_MMA(1, 1, At, B1); PG8_BAR; PG8_SCHED;
.LBB0_260:
	s_add_i32 s44, 0, 0x10000
	s_add_i32 s48, 0, 0x14000
	v_add_u32_e32 v146, s44, v149
	ds_read_b128 v[142:145], v146
	ds_read_b128 v[156:159], v146 offset:1024
	ds_read_b128 v[160:163], v146 offset:2048
	ds_read_b128 v[164:167], v146 offset:3072
	v_add_u32_e32 v146, s48, v149
	ds_read_b128 v[168:171], v146
	ds_read_b128 v[172:175], v146 offset:1024
	ds_read_b128 v[176:179], v146 offset:2048
	ds_read_b128 v[180:183], v146 offset:3072
	ds_read_b128 v[184:187], v155
	ds_read_b128 v[188:191], v155 offset:1024
	ds_read_b128 v[198:201], v155 offset:2048
	ds_read_b128 v[202:205], v155 offset:3072
	ds_read_b128 v[206:209], v155 offset:4096
	ds_read_b128 v[210:213], v155 offset:5120
	ds_read_b128 v[214:217], v155 offset:6144
	ds_read_b128 v[228:231], v155 offset:7168
	s_add_u32 s100, s10, 0xfff00000
	s_addc_u32 s101, s11, -1
	s_add_u32 s12, s10, 0xfff00080
	s_addc_u32 s13, s11, -1
	s_cmp_eq_u32 s42, 60
	s_cselect_b32 s15, s2, s13
	s_cselect_b32 s14, s3, s12
	s_cselect_b32 s13, s17, s41
	s_cselect_b32 s12, s23, s25
	s_add_i32 m0, s34, 0xc000
	s_mov_b32 m0, s38
	s_nop 0
	global_load_lds_dwordx4 v132, s[100:101]
	s_mov_b32 m0, s39
	s_nop 0
	global_load_lds_dwordx4 v130, s[100:101]
	s_add_i32 m0, s34, 0xc000
	s_nop 0
	global_load_lds_dwordx4 v138, s[10:11]
	s_add_i32 m0, s34, 0xe000
	s_nop 0
	global_load_lds_dwordx4 v140, s[10:11]
	s_waitcnt vmcnt(8)
	s_waitcnt lgkmcnt(0)
	s_barrier
	s_setprio 1
	s_waitcnt lgkmcnt(0)
	v_mfma_f32_16x16x32_bf16 v[124:127], v[142:145], v[184:187], v[124:127]
	v_mfma_f32_16x16x32_bf16 v[120:123], v[160:163], v[184:187], v[120:123]
	v_mfma_f32_16x16x32_bf16 v[108:111], v[142:145], v[198:201], v[108:111]
	v_mfma_f32_16x16x32_bf16 v[104:107], v[160:163], v[198:201], v[104:107]
	v_mfma_f32_16x16x32_bf16 v[92:95], v[142:145], v[206:209], v[92:95]
	v_mfma_f32_16x16x32_bf16 v[88:91], v[160:163], v[206:209], v[88:91]
	v_mfma_f32_16x16x32_bf16 v[76:79], v[142:145], v[214:217], v[76:79]
	v_mfma_f32_16x16x32_bf16 v[72:75], v[160:163], v[214:217], v[72:75]
	v_mfma_f32_16x16x32_bf16 v[124:127], v[156:159], v[188:191], v[124:127]
	v_mfma_f32_16x16x32_bf16 v[120:123], v[164:167], v[188:191], v[120:123]
	v_mfma_f32_16x16x32_bf16 v[108:111], v[156:159], v[202:205], v[108:111]
	v_mfma_f32_16x16x32_bf16 v[104:107], v[164:167], v[202:205], v[104:107]
	v_mfma_f32_16x16x32_bf16 v[92:95], v[156:159], v[210:213], v[92:95]
	v_mfma_f32_16x16x32_bf16 v[88:91], v[164:167], v[210:213], v[88:91]
	v_mfma_f32_16x16x32_bf16 v[76:79], v[156:159], v[228:231], v[76:79]
	v_mfma_f32_16x16x32_bf16 v[72:75], v[164:167], v[228:231], v[72:75]
	s_setprio 0
	s_setprio 1
	v_mfma_f32_16x16x32_bf16 v[116:119], v[168:171], v[184:187], v[116:119]
	v_mfma_f32_16x16x32_bf16 v[112:115], v[176:179], v[184:187], v[112:115]
	v_mfma_f32_16x16x32_bf16 v[100:103], v[168:171], v[198:201], v[100:103]
	v_mfma_f32_16x16x32_bf16 v[96:99], v[176:179], v[198:201], v[96:99]
	v_mfma_f32_16x16x32_bf16 v[84:87], v[168:171], v[206:209], v[84:87]
	v_mfma_f32_16x16x32_bf16 v[80:83], v[176:179], v[206:209], v[80:83]
	v_mfma_f32_16x16x32_bf16 v[68:71], v[168:171], v[214:217], v[68:71]
	v_mfma_f32_16x16x32_bf16 v[64:67], v[176:179], v[214:217], v[64:67]
	v_mfma_f32_16x16x32_bf16 v[116:119], v[172:175], v[188:191], v[116:119]
	v_mfma_f32_16x16x32_bf16 v[112:115], v[180:183], v[188:191], v[112:115]
	v_mfma_f32_16x16x32_bf16 v[100:103], v[172:175], v[202:205], v[100:103]
	v_mfma_f32_16x16x32_bf16 v[96:99], v[180:183], v[202:205], v[96:99]
	v_mfma_f32_16x16x32_bf16 v[84:87], v[172:175], v[210:213], v[84:87]
	v_mfma_f32_16x16x32_bf16 v[80:83], v[180:183], v[210:213], v[80:83]
	v_mfma_f32_16x16x32_bf16 v[68:71], v[172:175], v[228:231], v[68:71]
	v_mfma_f32_16x16x32_bf16 v[64:67], v[180:183], v[228:231], v[64:67]
	s_setprio 0
	s_barrier
	ds_read_b128 v[184:187], v155 offset:16384
	ds_read_b128 v[188:191], v155 offset:17408
	ds_read_b128 v[198:201], v155 offset:18432
	ds_read_b128 v[202:205], v155 offset:19456
	ds_read_b128 v[206:209], v155 offset:20480
	ds_read_b128 v[210:213], v155 offset:21504
	ds_read_b128 v[214:217], v155 offset:22528
	ds_read_b128 v[228:231], v155 offset:23552
	s_add_u32 s98, s12, 0x80
	s_addc_u32 s99, s13, 0
	s_add_i32 s44, s44, s7
	s_mov_b32 m0, s44
	s_nop 0
	global_load_lds_dwordx4 v196, s[12:13]
	s_add_i32 m0, s44, 0x2000
	s_add_u32 s46, s12, 0x100000
	s_addc_u32 s47, s13, 0
	s_add_i32 s44, s48, s7
	global_load_lds_dwordx4 v128, s[12:13]
	s_mov_b32 m0, s44
	s_nop 0
	global_load_lds_dwordx4 v196, s[46:47]
	s_add_i32 m0, s44, 0x2000
	s_nop 0
	global_load_lds_dwordx4 v128, s[46:47]
	s_waitcnt vmcnt(6)
	s_waitcnt lgkmcnt(0)
	s_barrier
; #define PG8_STAGE(bufoff, gbase, voff) do { _Pragma("unroll") for (int _i = 0; _i < 2; ++_i) \
;         __builtin_amdgcn_global_load_lds((const unsigned*)((const char*)(gbase) + (voff)[_i]), (LAS unsigned*)(lds + (bufoff) + ldsw + _i * 8192), 16, 0, 0); } while (0)
; #define PG8_LDA(dst, b, h) do { _Pragma("unroll") for (int m = 0; m < 4; ++m) _Pragma("unroll") for (int k = 0; k < 2; ++k) dst[m][k] = *(const LAS bf16x8*)(lds + PG8_SA(b, h) + aoff + m * 2048 + k * 1024); } while (0)
; #define PG8_LDB(dst, b, h) do { _Pragma("unroll") for (int n = 0; n < 2; ++n) _Pragma("unroll") for (int k = 0; k < 2; ++k) dst[n][k] = *(const LAS bf16x8*)(lds + PG8_SB(b, h) + boff + n * 2048 + k * 1024); } while (0)
; #define PG8_MMA(ai, bj, At, Bt) do { __builtin_amdgcn_s_setprio(1); _Pragma("unroll") for (int m = 0; m < 4; ++m) _Pragma("unroll") for (int n = 0; n < 2; ++n) _Pragma("unroll") for (int k = 0; k < 2; ++k) \
;         acc[ai][bj][m][n] = __builtin_amdgcn_mfma_f32_16x16x32_bf16(Bt[n][k], At[m][k], acc[ai][bj][m][n], 0, 0, 0); __builtin_amdgcn_s_setprio(0); } while (0)
; #define PG8_WAIT_V(n) asm volatile("s_waitcnt vmcnt(" #n ")" ::: "memory")
; #define PG8_WAIT_L(n) asm volatile("s_waitcnt lgkmcnt(" #n ")" ::: "memory")
; #define PG8_BAR __builtin_amdgcn_s_barrier()
; #define PG8_SCHED __builtin_amdgcn_sched_barrier(0)
; template <class Epi, class Sched, bool ALIGN_EPI = false, bool SP2 = false>
; __device__ __forceinline__ void gemm_phase(LAS unsigned char* lds, const Gemm g, const Sched& S, const Epi& E) {
;     ...
;             PG8_LDA(At, 0, 1); PG8_STAGE(PG8_SB(0, 0), b2, voffB); PG8_STAGE(PG8_SB(0, 1), b2 + hstep, voffB); PG8_STAGE(PG8_SA(0, 0), a2, voffA);
;             PG8_WAIT_V(8); PG8_WAIT_L(0); PG8_BAR; PG8_MMA(1, 0, At, B0); PG8_MMA(1, 1, At, B1); PG8_BAR; PG8_SCHED;
;             PG8_LDB(B0, 1, 0); PG8_LDB(B1, 1, 1); PG8_SCHED; PG8_LDA(At, 1, 0); PG8_STAGE(PG8_SA(0, 1), a2 + hstep, voffA);
;             PG8_WAIT_V(8); PG8_WAIT_L(0); PG8_BAR; PG8_MMA(0, 0, At, B0); PG8_MMA(0, 1, At, B1); PG8_BAR; PG8_SCHED;
	s_setprio 1
	s_waitcnt lgkmcnt(0)
	v_mfma_f32_16x16x32_bf16 v[60:63], v[142:145], v[184:187], v[60:63]
	v_mfma_f32_16x16x32_bf16 v[56:59], v[160:163], v[184:187], v[56:59]
	v_mfma_f32_16x16x32_bf16 v[44:47], v[142:145], v[198:201], v[44:47]
	v_mfma_f32_16x16x32_bf16 v[40:43], v[160:163], v[198:201], v[40:43]
	v_mfma_f32_16x16x32_bf16 v[28:31], v[142:145], v[206:209], v[28:31]
	v_mfma_f32_16x16x32_bf16 v[24:27], v[160:163], v[206:209], v[24:27]
	v_mfma_f32_16x16x32_bf16 v[12:15], v[142:145], v[214:217], v[12:15]
	v_mfma_f32_16x16x32_bf16 v[8:11], v[160:163], v[214:217], v[8:11]
	v_mfma_f32_16x16x32_bf16 v[60:63], v[156:159], v[188:191], v[60:63]
	v_mfma_f32_16x16x32_bf16 v[56:59], v[164:167], v[188:191], v[56:59]
	v_mfma_f32_16x16x32_bf16 v[44:47], v[156:159], v[202:205], v[44:47]
	v_mfma_f32_16x16x32_bf16 v[40:43], v[164:167], v[202:205], v[40:43]
	v_mfma_f32_16x16x32_bf16 v[28:31], v[156:159], v[210:213], v[28:31]
	v_mfma_f32_16x16x32_bf16 v[24:27], v[164:167], v[210:213], v[24:27]
	v_mfma_f32_16x16x32_bf16 v[12:15], v[156:159], v[228:231], v[12:15]
	v_mfma_f32_16x16x32_bf16 v[8:11], v[164:167], v[228:231], v[8:11]
	s_setprio 0
	s_setprio 1
	v_mfma_f32_16x16x32_bf16 v[52:55], v[168:171], v[184:187], v[52:55]
	v_mfma_f32_16x16x32_bf16 v[48:51], v[176:179], v[184:187], v[48:51]
	v_mfma_f32_16x16x32_bf16 v[36:39], v[168:171], v[198:201], v[36:39]
	v_mfma_f32_16x16x32_bf16 v[32:35], v[176:179], v[198:201], v[32:35]
	v_mfma_f32_16x16x32_bf16 v[20:23], v[168:171], v[206:209], v[20:23]
	v_mfma_f32_16x16x32_bf16 v[16:19], v[176:179], v[206:209], v[16:19]
	v_mfma_f32_16x16x32_bf16 v[4:7], v[168:171], v[214:217], v[4:7]
	v_mfma_f32_16x16x32_bf16 v[0:3], v[176:179], v[214:217], v[0:3]
	v_mfma_f32_16x16x32_bf16 v[52:55], v[172:175], v[188:191], v[52:55]
	v_mfma_f32_16x16x32_bf16 v[48:51], v[180:183], v[188:191], v[48:51]
	v_mfma_f32_16x16x32_bf16 v[36:39], v[172:175], v[202:205], v[36:39]
	v_mfma_f32_16x16x32_bf16 v[32:35], v[180:183], v[202:205], v[32:35]
	v_mfma_f32_16x16x32_bf16 v[20:23], v[172:175], v[210:213], v[20:23]
	v_mfma_f32_16x16x32_bf16 v[16:19], v[180:183], v[210:213], v[16:19]
	v_mfma_f32_16x16x32_bf16 v[4:7], v[172:175], v[228:231], v[4:7]
	v_mfma_f32_16x16x32_bf16 v[0:3], v[180:183], v[228:231], v[0:3]
	s_setprio 0
	s_barrier
	s_add_i32 s44, 0, 0x18000
	s_add_i32 s46, 0, 0x1c000
	v_add_u32_e32 v164, s44, v149
	v_add_u32_e32 v180, s46, v149
	ds_read_b128 v[142:145], v164
	ds_read_b128 v[156:159], v164 offset:1024
	ds_read_b128 v[160:163], v164 offset:2048
	ds_read_b128 v[164:167], v164 offset:3072
	ds_read_b128 v[168:171], v180
	ds_read_b128 v[172:175], v180 offset:1024
	ds_read_b128 v[176:179], v180 offset:2048
	ds_read_b128 v[180:183], v180 offset:3072
	ds_read_b128 v[184:187], v155 offset:32768
	ds_read_b128 v[188:191], v155 offset:33792
	ds_read_b128 v[198:201], v155 offset:34816
	ds_read_b128 v[202:205], v155 offset:35840
	ds_read_b128 v[206:209], v155 offset:36864
	ds_read_b128 v[210:213], v155 offset:37888
	ds_read_b128 v[214:217], v155 offset:38912
	ds_read_b128 v[228:231], v155 offset:39936
	s_mov_b32 m0, s34
	s_nop 0
	global_load_lds_dwordx4 v132, s[14:15]
	s_mov_b32 m0, s35
	s_nop 0
	global_load_lds_dwordx4 v130, s[14:15]
	s_add_u32 s14, s14, 0x100000
	s_addc_u32 s15, s15, 0
	s_mov_b32 m0, s36
	s_nop 0
	global_load_lds_dwordx4 v132, s[14:15]
	s_mov_b32 m0, s37
	s_nop 0
	global_load_lds_dwordx4 v130, s[14:15]
	s_waitcnt vmcnt(8)
	s_waitcnt lgkmcnt(0)
	s_barrier
; #define PG8_STAGE(bufoff, gbase, voff) do { _Pragma("unroll") for (int _i = 0; _i < 2; ++_i) \
;         __builtin_amdgcn_global_load_lds((const unsigned*)((const char*)(gbase) + (voff)[_i]), (LAS unsigned*)(lds + (bufoff) + ldsw + _i * 8192), 16, 0, 0); } while (0)
; #define PG8_LDA(dst, b, h) do { _Pragma("unroll") for (int m = 0; m < 4; ++m) _Pragma("unroll") for (int k = 0; k < 2; ++k) dst[m][k] = *(const LAS bf16x8*)(lds + PG8_SA(b, h) + aoff + m * 2048 + k * 1024); } while (0)
; #define PG8_MMA(ai, bj, At, Bt) do { __builtin_amdgcn_s_setprio(1); _Pragma("unroll") for (int m = 0; m < 4; ++m) _Pragma("unroll") for (int n = 0; n < 2; ++n) _Pragma("unroll") for (int k = 0; k < 2; ++k) \
;         acc[ai][bj][m][n] = __builtin_amdgcn_mfma_f32_16x16x32_bf16(Bt[n][k], At[m][k], acc[ai][bj][m][n], 0, 0, 0); __builtin_amdgcn_s_setprio(0); } while (0)
; #define PG8_WAIT_V(n) asm volatile("s_waitcnt vmcnt(" #n ")" ::: "memory")
; #define PG8_WAIT_L(n) asm volatile("s_waitcnt lgkmcnt(" #n ")" ::: "memory")
; #define PG8_BAR __builtin_amdgcn_s_barrier()
; #define PG8_SCHED __builtin_amdgcn_sched_barrier(0)
; template <class Epi, class Sched, bool ALIGN_EPI = false, bool SP2 = false>
; __device__ __forceinline__ void gemm_phase(LAS unsigned char* lds, const Gemm g, const Sched& S, const Epi& E) {
;     ...
;             PG8_WAIT_V(8); PG8_WAIT_L(0); PG8_BAR; PG8_MMA(0, 0, At, B0); PG8_MMA(0, 1, At, B1); PG8_BAR; PG8_SCHED;
;             PG8_LDA(At, 1, 1); PG8_STAGE(PG8_SB(1, 0), b3, voffB); PG8_STAGE(PG8_SB(1, 1), b3 + hstep, voffB); PG8_STAGE(PG8_SA(1, 0), a3, voffA);
;             PG8_WAIT_V(8); PG8_WAIT_L(0); PG8_BAR; PG8_MMA(1, 0, At, B0); PG8_MMA(1, 1, At, B1); PG8_BAR; PG8_SCHED;
;     ...
;         if constexpr (ALIGN_EPI) { if (wr == 0) PG8_BAR; }
	s_setprio 1
	s_waitcnt lgkmcnt(0)
	v_mfma_f32_16x16x32_bf16 v[124:127], v[142:145], v[184:187], v[124:127]
	v_mfma_f32_16x16x32_bf16 v[120:123], v[160:163], v[184:187], v[120:123]
	v_mfma_f32_16x16x32_bf16 v[108:111], v[142:145], v[198:201], v[108:111]
	v_mfma_f32_16x16x32_bf16 v[104:107], v[160:163], v[198:201], v[104:107]
	v_mfma_f32_16x16x32_bf16 v[92:95], v[142:145], v[206:209], v[92:95]
	v_mfma_f32_16x16x32_bf16 v[88:91], v[160:163], v[206:209], v[88:91]
	v_mfma_f32_16x16x32_bf16 v[76:79], v[142:145], v[214:217], v[76:79]
	v_mfma_f32_16x16x32_bf16 v[72:75], v[160:163], v[214:217], v[72:75]
	v_mfma_f32_16x16x32_bf16 v[124:127], v[156:159], v[188:191], v[124:127]
	v_mfma_f32_16x16x32_bf16 v[120:123], v[164:167], v[188:191], v[120:123]
	v_mfma_f32_16x16x32_bf16 v[108:111], v[156:159], v[202:205], v[108:111]
	v_mfma_f32_16x16x32_bf16 v[104:107], v[164:167], v[202:205], v[104:107]
	v_mfma_f32_16x16x32_bf16 v[92:95], v[156:159], v[210:213], v[92:95]
	v_mfma_f32_16x16x32_bf16 v[88:91], v[164:167], v[210:213], v[88:91]
	v_mfma_f32_16x16x32_bf16 v[76:79], v[156:159], v[228:231], v[76:79]
	v_mfma_f32_16x16x32_bf16 v[72:75], v[164:167], v[228:231], v[72:75]
	s_setprio 0
	s_setprio 1
	v_mfma_f32_16x16x32_bf16 v[116:119], v[168:171], v[184:187], v[116:119]
	v_mfma_f32_16x16x32_bf16 v[112:115], v[176:179], v[184:187], v[112:115]
	v_mfma_f32_16x16x32_bf16 v[100:103], v[168:171], v[198:201], v[100:103]
	v_mfma_f32_16x16x32_bf16 v[96:99], v[176:179], v[198:201], v[96:99]
	v_mfma_f32_16x16x32_bf16 v[84:87], v[168:171], v[206:209], v[84:87]
	v_mfma_f32_16x16x32_bf16 v[80:83], v[176:179], v[206:209], v[80:83]
	v_mfma_f32_16x16x32_bf16 v[68:71], v[168:171], v[214:217], v[68:71]
	v_mfma_f32_16x16x32_bf16 v[64:67], v[176:179], v[214:217], v[64:67]
	v_mfma_f32_16x16x32_bf16 v[116:119], v[172:175], v[188:191], v[116:119]
	v_mfma_f32_16x16x32_bf16 v[112:115], v[180:183], v[188:191], v[112:115]
	v_mfma_f32_16x16x32_bf16 v[100:103], v[172:175], v[202:205], v[100:103]
	v_mfma_f32_16x16x32_bf16 v[96:99], v[180:183], v[202:205], v[96:99]
	v_mfma_f32_16x16x32_bf16 v[84:87], v[172:175], v[210:213], v[84:87]
	v_mfma_f32_16x16x32_bf16 v[80:83], v[180:183], v[210:213], v[80:83]
	v_mfma_f32_16x16x32_bf16 v[68:71], v[172:175], v[228:231], v[68:71]
	v_mfma_f32_16x16x32_bf16 v[64:67], v[180:183], v[228:231], v[64:67]
	s_setprio 0
	s_barrier
	ds_read_b128 v[184:187], v155 offset:49152
	ds_read_b128 v[188:191], v155 offset:50176
	ds_read_b128 v[198:201], v155 offset:51200
	ds_read_b128 v[202:205], v155 offset:52224
	ds_read_b128 v[206:209], v155 offset:53248
	ds_read_b128 v[210:213], v155 offset:54272
	ds_read_b128 v[214:217], v155 offset:55296
	ds_read_b128 v[228:231], v155 offset:56320
	s_add_i32 s14, s44, s7
	s_mov_b32 m0, s14
	s_nop 0
	global_load_lds_dwordx4 v196, s[98:99]
	s_add_i32 m0, s14, 0x2000
	s_add_u32 s12, s12, 0x100080
	s_addc_u32 s13, s13, 0
	s_add_i32 s14, s46, s7
	global_load_lds_dwordx4 v128, s[98:99]
	s_mov_b32 m0, s14
	s_nop 0
	global_load_lds_dwordx4 v196, s[12:13]
	s_add_i32 m0, s14, 0x2000
	s_nop 0
	global_load_lds_dwordx4 v128, s[12:13]
	s_waitcnt vmcnt(6)
	s_waitcnt lgkmcnt(0)
	s_barrier
	s_setprio 1
	s_waitcnt lgkmcnt(0)
	v_mfma_f32_16x16x32_bf16 v[60:63], v[142:145], v[184:187], v[60:63]
	v_mfma_f32_16x16x32_bf16 v[56:59], v[160:163], v[184:187], v[56:59]
	v_mfma_f32_16x16x32_bf16 v[44:47], v[142:145], v[198:201], v[44:47]
	v_mfma_f32_16x16x32_bf16 v[40:43], v[160:163], v[198:201], v[40:43]
	v_mfma_f32_16x16x32_bf16 v[28:31], v[142:145], v[206:209], v[28:31]
	v_mfma_f32_16x16x32_bf16 v[24:27], v[160:163], v[206:209], v[24:27]
	v_mfma_f32_16x16x32_bf16 v[12:15], v[142:145], v[214:217], v[12:15]
	v_mfma_f32_16x16x32_bf16 v[8:11], v[160:163], v[214:217], v[8:11]
	v_mfma_f32_16x16x32_bf16 v[60:63], v[156:159], v[188:191], v[60:63]
	v_mfma_f32_16x16x32_bf16 v[56:59], v[164:167], v[188:191], v[56:59]
	v_mfma_f32_16x16x32_bf16 v[44:47], v[156:159], v[202:205], v[44:47]
	v_mfma_f32_16x16x32_bf16 v[40:43], v[164:167], v[202:205], v[40:43]
	v_mfma_f32_16x16x32_bf16 v[28:31], v[156:159], v[210:213], v[28:31]
	v_mfma_f32_16x16x32_bf16 v[24:27], v[164:167], v[210:213], v[24:27]
	v_mfma_f32_16x16x32_bf16 v[12:15], v[156:159], v[228:231], v[12:15]
	v_mfma_f32_16x16x32_bf16 v[8:11], v[164:167], v[228:231], v[8:11]
	s_setprio 0
	s_setprio 1
	v_mfma_f32_16x16x32_bf16 v[52:55], v[168:171], v[184:187], v[52:55]
	v_mfma_f32_16x16x32_bf16 v[48:51], v[176:179], v[184:187], v[48:51]
	v_mfma_f32_16x16x32_bf16 v[36:39], v[168:171], v[198:201], v[36:39]
	v_mfma_f32_16x16x32_bf16 v[32:35], v[176:179], v[198:201], v[32:35]
	v_mfma_f32_16x16x32_bf16 v[20:23], v[168:171], v[206:209], v[20:23]
	v_mfma_f32_16x16x32_bf16 v[16:19], v[176:179], v[206:209], v[16:19]
	v_mfma_f32_16x16x32_bf16 v[4:7], v[168:171], v[214:217], v[4:7]
	v_mfma_f32_16x16x32_bf16 v[0:3], v[176:179], v[214:217], v[0:3]
	v_mfma_f32_16x16x32_bf16 v[52:55], v[172:175], v[188:191], v[52:55]
	v_mfma_f32_16x16x32_bf16 v[48:51], v[180:183], v[188:191], v[48:51]
	v_mfma_f32_16x16x32_bf16 v[36:39], v[172:175], v[202:205], v[36:39]
	v_mfma_f32_16x16x32_bf16 v[32:35], v[180:183], v[202:205], v[32:35]
	v_mfma_f32_16x16x32_bf16 v[20:23], v[172:175], v[210:213], v[20:23]
	v_mfma_f32_16x16x32_bf16 v[16:19], v[180:183], v[210:213], v[16:19]
	v_mfma_f32_16x16x32_bf16 v[4:7], v[172:175], v[228:231], v[4:7]
	v_mfma_f32_16x16x32_bf16 v[0:3], v[180:183], v[228:231], v[0:3]
	s_setprio 0
	s_barrier
	s_add_i32 s42, s42, 2
	s_add_u32 s10, s10, 0x100
	s_addc_u32 s11, s11, 0
	s_add_u32 s25, s25, 0x100
	s_addc_u32 s41, s41, 0
	s_cmp_gt_u32 s42, 61
	s_cbranch_scc0 .LBB0_260
	s_and_b64 vcc, exec, s[20:21]
	s_cbranch_vccz .LBB0_263
	s_barrier

; #define PG8_STAGE(bufoff, gbase, voff) do { _Pragma("unroll") for (int _i = 0; _i < 2; ++_i) \
;         __builtin_amdgcn_global_load_lds((const unsigned*)((const char*)(gbase) + (voff)[_i]), (LAS unsigned*)(lds + (bufoff) + ldsw + _i * 8192), 16, 0, 0); } while (0)
; #define PG8_LDA(dst, b, h) do { _Pragma("unroll") for (int m = 0; m < 4; ++m) _Pragma("unroll") for (int k = 0; k < 2; ++k) dst[m][k] = *(const LAS bf16x8*)(lds + PG8_SA(b, h) + aoff + m * 2048 + k * 1024); } while (0)
; #define PG8_LDB(dst, b, h) do { _Pragma("unroll") for (int n = 0; n < 2; ++n) _Pragma("unroll") for (int k = 0; k < 2; ++k) dst[n][k] = *(const LAS bf16x8*)(lds + PG8_SB(b, h) + boff + n * 2048 + k * 1024); } while (0)
; #define PG8_MMA(ai, bj, At, Bt) do { __builtin_amdgcn_s_setprio(1); _Pragma("unroll") for (int m = 0; m < 4; ++m) _Pragma("unroll") for (int n = 0; n < 2; ++n) _Pragma("unroll") for (int k = 0; k < 2; ++k) \
;         acc[ai][bj][m][n] = __builtin_amdgcn_mfma_f32_16x16x32_bf16(Bt[n][k], At[m][k], acc[ai][bj][m][n], 0, 0, 0); __builtin_amdgcn_s_setprio(0); } while (0)
; #define PG8_WAIT_V(n) asm volatile("s_waitcnt vmcnt(" #n ")" ::: "memory")
; #define PG8_WAIT_L(n) asm volatile("s_waitcnt lgkmcnt(" #n ")" ::: "memory")
; #define PG8_BAR __builtin_amdgcn_s_barrier()
; #define PG8_SCHED __builtin_amdgcn_sched_barrier(0)
; template <class Epi, class Sched, bool ALIGN_EPI = false, bool SP2 = false>
; __device__ __forceinline__ void gemm_phase(LAS unsigned char* lds, const Gemm g, const Sched& S, const Epi& E) {
;     ...
;             const char* a1 = cA + (size_t)(t + 1) * kstep;
;             const char* a2 = last ? nA : cA + (size_t)(t + 2) * kstep; const char* b2 = last ? nB : cB + (size_t)(t + 2) * kstep;
;             const char* a3 = a2 + kstep; const char* b3 = b2 + kstep;
;             if (last && has_next) S.a_ready(nxt);
;             if constexpr (SP2) {
;             PG8_LDB(B0, 0, 0); PG8_LDB(B1, 0, 1); PG8_SCHED; PG8_LDA(At, 0, 0); PG8_STAGE(PG8_SA(1, 1), a1 + hstep, voffA);
;             PG8_WAIT_V(8); PG8_WAIT_L(0); PG8_BAR; PG8_MMA(0, 0, At, B0); PG8_MMA(0, 1, At, B1); PG8_BAR; PG8_SCHED;
;             PG8_LDA(At, 0, 1); PG8_STAGE(PG8_SB(0, 0), b2, voffB); PG8_STAGE(PG8_SB(0, 1), b2 + hstep, voffB); PG8_STAGE(PG8_SA(0, 0), a2, voffA);
;             PG8_WAIT_V(8); PG8_WAIT_L(0); PG8_BAR; PG8_MMA(1, 0, At, B0); PG8_MMA(1, 1, At, B1); PG8_BAR; PG8_SCHED;
.LBB0_424:
	s_add_i32 s48, 0, 0x10000
	s_add_i32 s90, 0, 0x14000
	v_add_u32_e32 v146, s48, v149
	ds_read_b128 v[142:145], v146
	ds_read_b128 v[156:159], v146 offset:1024
	ds_read_b128 v[160:163], v146 offset:2048
	ds_read_b128 v[164:167], v146 offset:3072
	v_add_u32_e32 v146, s90, v149
	ds_read_b128 v[168:171], v146
	ds_read_b128 v[172:175], v146 offset:1024
	ds_read_b128 v[176:179], v146 offset:2048
	ds_read_b128 v[180:183], v146 offset:3072
	ds_read_b128 v[184:187], v155
	ds_read_b128 v[188:191], v155 offset:1024
	ds_read_b128 v[198:201], v155 offset:2048
	ds_read_b128 v[202:205], v155 offset:3072
	ds_read_b128 v[206:209], v155 offset:4096
	ds_read_b128 v[210:213], v155 offset:5120
	ds_read_b128 v[214:217], v155 offset:6144
	ds_read_b128 v[228:231], v155 offset:7168
	s_add_u32 s100, s10, 0xfff00000
	s_addc_u32 s101, s11, -1
	s_add_u32 s12, s10, 0xfff00080
	s_addc_u32 s13, s11, -1
	s_cmp_eq_u32 s42, 60
	s_cselect_b32 s15, s2, s13
	s_cselect_b32 s14, s3, s12
	s_cselect_b32 s13, s17, s41
	s_cselect_b32 s12, s23, s25
	s_add_i32 m0, s34, 0xc000
	s_mov_b32 m0, s38
	s_nop 0
	global_load_lds_dwordx4 v128, s[100:101]
	s_mov_b32 m0, s39
	s_nop 0
	global_load_lds_dwordx4 v130, s[100:101]
	s_add_i32 m0, s34, 0xc000
	s_nop 0
	global_load_lds_dwordx4 v138, s[10:11]
	s_add_i32 m0, s34, 0xe000
	s_nop 0
	global_load_lds_dwordx4 v140, s[10:11]
	s_waitcnt vmcnt(8)
	s_waitcnt lgkmcnt(0)
	s_barrier
	s_setprio 1
	s_waitcnt lgkmcnt(0)
	v_mfma_f32_16x16x32_bf16 v[124:127], v[142:145], v[184:187], v[124:127]
	v_mfma_f32_16x16x32_bf16 v[120:123], v[160:163], v[184:187], v[120:123]
	v_mfma_f32_16x16x32_bf16 v[108:111], v[142:145], v[198:201], v[108:111]
	v_mfma_f32_16x16x32_bf16 v[104:107], v[160:163], v[198:201], v[104:107]
	v_mfma_f32_16x16x32_bf16 v[92:95], v[142:145], v[206:209], v[92:95]
	v_mfma_f32_16x16x32_bf16 v[88:91], v[160:163], v[206:209], v[88:91]
	v_mfma_f32_16x16x32_bf16 v[76:79], v[142:145], v[214:217], v[76:79]
	v_mfma_f32_16x16x32_bf16 v[72:75], v[160:163], v[214:217], v[72:75]
	v_mfma_f32_16x16x32_bf16 v[124:127], v[156:159], v[188:191], v[124:127]
	v_mfma_f32_16x16x32_bf16 v[120:123], v[164:167], v[188:191], v[120:123]
	v_mfma_f32_16x16x32_bf16 v[108:111], v[156:159], v[202:205], v[108:111]
	v_mfma_f32_16x16x32_bf16 v[104:107], v[164:167], v[202:205], v[104:107]
	v_mfma_f32_16x16x32_bf16 v[92:95], v[156:159], v[210:213], v[92:95]
	v_mfma_f32_16x16x32_bf16 v[88:91], v[164:167], v[210:213], v[88:91]
	v_mfma_f32_16x16x32_bf16 v[76:79], v[156:159], v[228:231], v[76:79]
	v_mfma_f32_16x16x32_bf16 v[72:75], v[164:167], v[228:231], v[72:75]
	s_setprio 0
	s_setprio 1
	v_mfma_f32_16x16x32_bf16 v[116:119], v[168:171], v[184:187], v[116:119]
	v_mfma_f32_16x16x32_bf16 v[112:115], v[176:179], v[184:187], v[112:115]
	v_mfma_f32_16x16x32_bf16 v[100:103], v[168:171], v[198:201], v[100:103]
	v_mfma_f32_16x16x32_bf16 v[96:99], v[176:179], v[198:201], v[96:99]
	v_mfma_f32_16x16x32_bf16 v[84:87], v[168:171], v[206:209], v[84:87]
	v_mfma_f32_16x16x32_bf16 v[80:83], v[176:179], v[206:209], v[80:83]
	v_mfma_f32_16x16x32_bf16 v[68:71], v[168:171], v[214:217], v[68:71]
	v_mfma_f32_16x16x32_bf16 v[64:67], v[176:179], v[214:217], v[64:67]
	v_mfma_f32_16x16x32_bf16 v[116:119], v[172:175], v[188:191], v[116:119]
	v_mfma_f32_16x16x32_bf16 v[112:115], v[180:183], v[188:191], v[112:115]
	v_mfma_f32_16x16x32_bf16 v[100:103], v[172:175], v[202:205], v[100:103]
	v_mfma_f32_16x16x32_bf16 v[96:99], v[180:183], v[202:205], v[96:99]
	v_mfma_f32_16x16x32_bf16 v[84:87], v[172:175], v[210:213], v[84:87]
	v_mfma_f32_16x16x32_bf16 v[80:83], v[180:183], v[210:213], v[80:83]
	v_mfma_f32_16x16x32_bf16 v[68:71], v[172:175], v[228:231], v[68:71]
	v_mfma_f32_16x16x32_bf16 v[64:67], v[180:183], v[228:231], v[64:67]
	s_setprio 0
	s_barrier
	ds_read_b128 v[184:187], v155 offset:16384
	ds_read_b128 v[188:191], v155 offset:17408
	ds_read_b128 v[198:201], v155 offset:18432
	ds_read_b128 v[202:205], v155 offset:19456
	ds_read_b128 v[206:209], v155 offset:20480
	ds_read_b128 v[210:213], v155 offset:21504
	ds_read_b128 v[214:217], v155 offset:22528
	ds_read_b128 v[228:231], v155 offset:23552
	s_add_u32 s98, s12, 0x80
	s_addc_u32 s99, s13, 0
	s_add_i32 s44, s48, s7
	s_mov_b32 m0, s44
	s_nop 0
	global_load_lds_dwordx4 v196, s[12:13]
	s_add_i32 m0, s44, 0x2000
	s_add_u32 s46, s12, 0x100000
	s_addc_u32 s47, s13, 0
	s_add_i32 s44, s90, s7
	global_load_lds_dwordx4 v132, s[12:13]
	s_mov_b32 m0, s44
	s_nop 0
	global_load_lds_dwordx4 v196, s[46:47]
	s_add_i32 m0, s44, 0x2000
	s_nop 0
	global_load_lds_dwordx4 v132, s[46:47]
	s_waitcnt vmcnt(6)
	s_waitcnt lgkmcnt(0)
	s_barrier
; #define PG8_STAGE(bufoff, gbase, voff) do { _Pragma("unroll") for (int _i = 0; _i < 2; ++_i) \
;         __builtin_amdgcn_global_load_lds((const unsigned*)((const char*)(gbase) + (voff)[_i]), (LAS unsigned*)(lds + (bufoff) + ldsw + _i * 8192), 16, 0, 0); } while (0)
; #define PG8_LDA(dst, b, h) do { _Pragma("unroll") for (int m = 0; m < 4; ++m) _Pragma("unroll") for (int k = 0; k < 2; ++k) dst[m][k] = *(const LAS bf16x8*)(lds + PG8_SA(b, h) + aoff + m * 2048 + k * 1024); } while (0)
; #define PG8_LDB(dst, b, h) do { _Pragma("unroll") for (int n = 0; n < 2; ++n) _Pragma("unroll") for (int k = 0; k < 2; ++k) dst[n][k] = *(const LAS bf16x8*)(lds + PG8_SB(b, h) + boff + n * 2048 + k * 1024); } while (0)
; #define PG8_MMA(ai, bj, At, Bt) do { __builtin_amdgcn_s_setprio(1); _Pragma("unroll") for (int m = 0; m < 4; ++m) _Pragma("unroll") for (int n = 0; n < 2; ++n) _Pragma("unroll") for (int k = 0; k < 2; ++k) \
;         acc[ai][bj][m][n] = __builtin_amdgcn_mfma_f32_16x16x32_bf16(Bt[n][k], At[m][k], acc[ai][bj][m][n], 0, 0, 0); __builtin_amdgcn_s_setprio(0); } while (0)
; #define PG8_WAIT_V(n) asm volatile("s_waitcnt vmcnt(" #n ")" ::: "memory")
; #define PG8_WAIT_L(n) asm volatile("s_waitcnt lgkmcnt(" #n ")" ::: "memory")
; #define PG8_BAR __builtin_amdgcn_s_barrier()
; #define PG8_SCHED __builtin_amdgcn_sched_barrier(0)
; template <class Epi, class Sched, bool ALIGN_EPI = false, bool SP2 = false>
; __device__ __forceinline__ void gemm_phase(LAS unsigned char* lds, const Gemm g, const Sched& S, const Epi& E) {
;     ...
;             PG8_LDA(At, 0, 1); PG8_STAGE(PG8_SB(0, 0), b2, voffB); PG8_STAGE(PG8_SB(0, 1), b2 + hstep, voffB); PG8_STAGE(PG8_SA(0, 0), a2, voffA);
;             PG8_WAIT_V(8); PG8_WAIT_L(0); PG8_BAR; PG8_MMA(1, 0, At, B0); PG8_MMA(1, 1, At, B1); PG8_BAR; PG8_SCHED;
;             PG8_LDB(B0, 1, 0); PG8_LDB(B1, 1, 1); PG8_SCHED; PG8_LDA(At, 1, 0); PG8_STAGE(PG8_SA(0, 1), a2 + hstep, voffA);
;             PG8_WAIT_V(8); PG8_WAIT_L(0); PG8_BAR; PG8_MMA(0, 0, At, B0); PG8_MMA(0, 1, At, B1); PG8_BAR; PG8_SCHED;
	s_setprio 1
	s_waitcnt lgkmcnt(0)
	v_mfma_f32_16x16x32_bf16 v[60:63], v[142:145], v[184:187], v[60:63]
	v_mfma_f32_16x16x32_bf16 v[56:59], v[160:163], v[184:187], v[56:59]
	v_mfma_f32_16x16x32_bf16 v[44:47], v[142:145], v[198:201], v[44:47]
	v_mfma_f32_16x16x32_bf16 v[40:43], v[160:163], v[198:201], v[40:43]
	v_mfma_f32_16x16x32_bf16 v[28:31], v[142:145], v[206:209], v[28:31]
	v_mfma_f32_16x16x32_bf16 v[24:27], v[160:163], v[206:209], v[24:27]
	v_mfma_f32_16x16x32_bf16 v[12:15], v[142:145], v[214:217], v[12:15]
	v_mfma_f32_16x16x32_bf16 v[8:11], v[160:163], v[214:217], v[8:11]
	v_mfma_f32_16x16x32_bf16 v[60:63], v[156:159], v[188:191], v[60:63]
	v_mfma_f32_16x16x32_bf16 v[56:59], v[164:167], v[188:191], v[56:59]
	v_mfma_f32_16x16x32_bf16 v[44:47], v[156:159], v[202:205], v[44:47]
	v_mfma_f32_16x16x32_bf16 v[40:43], v[164:167], v[202:205], v[40:43]
	v_mfma_f32_16x16x32_bf16 v[28:31], v[156:159], v[210:213], v[28:31]
	v_mfma_f32_16x16x32_bf16 v[24:27], v[164:167], v[210:213], v[24:27]
	v_mfma_f32_16x16x32_bf16 v[12:15], v[156:159], v[228:231], v[12:15]
	v_mfma_f32_16x16x32_bf16 v[8:11], v[164:167], v[228:231], v[8:11]
	s_setprio 0
	s_setprio 1
	v_mfma_f32_16x16x32_bf16 v[52:55], v[168:171], v[184:187], v[52:55]
	v_mfma_f32_16x16x32_bf16 v[48:51], v[176:179], v[184:187], v[48:51]
	v_mfma_f32_16x16x32_bf16 v[36:39], v[168:171], v[198:201], v[36:39]
	v_mfma_f32_16x16x32_bf16 v[32:35], v[176:179], v[198:201], v[32:35]
	v_mfma_f32_16x16x32_bf16 v[20:23], v[168:171], v[206:209], v[20:23]
	v_mfma_f32_16x16x32_bf16 v[16:19], v[176:179], v[206:209], v[16:19]
	v_mfma_f32_16x16x32_bf16 v[4:7], v[168:171], v[214:217], v[4:7]
	v_mfma_f32_16x16x32_bf16 v[0:3], v[176:179], v[214:217], v[0:3]
	v_mfma_f32_16x16x32_bf16 v[52:55], v[172:175], v[188:191], v[52:55]
	v_mfma_f32_16x16x32_bf16 v[48:51], v[180:183], v[188:191], v[48:51]
	v_mfma_f32_16x16x32_bf16 v[36:39], v[172:175], v[202:205], v[36:39]
	v_mfma_f32_16x16x32_bf16 v[32:35], v[180:183], v[202:205], v[32:35]
	v_mfma_f32_16x16x32_bf16 v[20:23], v[172:175], v[210:213], v[20:23]
	v_mfma_f32_16x16x32_bf16 v[16:19], v[180:183], v[210:213], v[16:19]
	v_mfma_f32_16x16x32_bf16 v[4:7], v[172:175], v[228:231], v[4:7]
	v_mfma_f32_16x16x32_bf16 v[0:3], v[180:183], v[228:231], v[0:3]
	s_setprio 0
	s_barrier
	s_add_i32 s91, 0, 0x18000
	s_add_i32 s58, 0, 0x1c000
	v_add_u32_e32 v164, s91, v149
	v_add_u32_e32 v180, s58, v149
	ds_read_b128 v[142:145], v164
	ds_read_b128 v[156:159], v164 offset:1024
	ds_read_b128 v[160:163], v164 offset:2048
	ds_read_b128 v[164:167], v164 offset:3072
	ds_read_b128 v[168:171], v180
	ds_read_b128 v[172:175], v180 offset:1024
	ds_read_b128 v[176:179], v180 offset:2048
	ds_read_b128 v[180:183], v180 offset:3072
	ds_read_b128 v[184:187], v155 offset:32768
	ds_read_b128 v[188:191], v155 offset:33792
	ds_read_b128 v[198:201], v155 offset:34816
	ds_read_b128 v[202:205], v155 offset:35840
	ds_read_b128 v[206:209], v155 offset:36864
	ds_read_b128 v[210:213], v155 offset:37888
	ds_read_b128 v[214:217], v155 offset:38912
	ds_read_b128 v[228:231], v155 offset:39936
	s_mov_b32 m0, s34
	s_nop 0
	global_load_lds_dwordx4 v128, s[14:15]
	s_mov_b32 m0, s35
	s_nop 0
	global_load_lds_dwordx4 v130, s[14:15]
	s_add_u32 s14, s14, 0x100000
	s_addc_u32 s15, s15, 0
	s_mov_b32 m0, s36
	s_nop 0
	global_load_lds_dwordx4 v128, s[14:15]
	s_mov_b32 m0, s37
	s_nop 0
	global_load_lds_dwordx4 v130, s[14:15]
	s_waitcnt vmcnt(8)
	s_waitcnt lgkmcnt(0)
	s_barrier
; #define PG8_STAGE(bufoff, gbase, voff) do { _Pragma("unroll") for (int _i = 0; _i < 2; ++_i) \
;         __builtin_amdgcn_global_load_lds((const unsigned*)((const char*)(gbase) + (voff)[_i]), (LAS unsigned*)(lds + (bufoff) + ldsw + _i * 8192), 16, 0, 0); } while (0)
; #define PG8_LDA(dst, b, h) do { _Pragma("unroll") for (int m = 0; m < 4; ++m) _Pragma("unroll") for (int k = 0; k < 2; ++k) dst[m][k] = *(const LAS bf16x8*)(lds + PG8_SA(b, h) + aoff + m * 2048 + k * 1024); } while (0)
; #define PG8_MMA(ai, bj, At, Bt) do { __builtin_amdgcn_s_setprio(1); _Pragma("unroll") for (int m = 0; m < 4; ++m) _Pragma("unroll") for (int n = 0; n < 2; ++n) _Pragma("unroll") for (int k = 0; k < 2; ++k) \
;         acc[ai][bj][m][n] = __builtin_amdgcn_mfma_f32_16x16x32_bf16(Bt[n][k], At[m][k], acc[ai][bj][m][n], 0, 0, 0); __builtin_amdgcn_s_setprio(0); } while (0)
; #define PG8_WAIT_V(n) asm volatile("s_waitcnt vmcnt(" #n ")" ::: "memory")
; #define PG8_WAIT_L(n) asm volatile("s_waitcnt lgkmcnt(" #n ")" ::: "memory")
; #define PG8_BAR __builtin_amdgcn_s_barrier()
; #define PG8_SCHED __builtin_amdgcn_sched_barrier(0)
; template <class Epi, class Sched, bool ALIGN_EPI = false, bool SP2 = false>
; __device__ __forceinline__ void gemm_phase(LAS unsigned char* lds, const Gemm g, const Sched& S, const Epi& E) {
;     ...
;             PG8_WAIT_V(8); PG8_WAIT_L(0); PG8_BAR; PG8_MMA(0, 0, At, B0); PG8_MMA(0, 1, At, B1); PG8_BAR; PG8_SCHED;
;             PG8_LDA(At, 1, 1); PG8_STAGE(PG8_SB(1, 0), b3, voffB); PG8_STAGE(PG8_SB(1, 1), b3 + hstep, voffB); PG8_STAGE(PG8_SA(1, 0), a3, voffA);
;             PG8_WAIT_V(8); PG8_WAIT_L(0); PG8_BAR; PG8_MMA(1, 0, At, B0); PG8_MMA(1, 1, At, B1); PG8_BAR; PG8_SCHED;
;     ...
;         if constexpr (ALIGN_EPI) { if (wr == 0) PG8_BAR; }
	s_setprio 1
	s_waitcnt lgkmcnt(0)
	v_mfma_f32_16x16x32_bf16 v[124:127], v[142:145], v[184:187], v[124:127]
	v_mfma_f32_16x16x32_bf16 v[120:123], v[160:163], v[184:187], v[120:123]
	v_mfma_f32_16x16x32_bf16 v[108:111], v[142:145], v[198:201], v[108:111]
	v_mfma_f32_16x16x32_bf16 v[104:107], v[160:163], v[198:201], v[104:107]
	v_mfma_f32_16x16x32_bf16 v[92:95], v[142:145], v[206:209], v[92:95]
	v_mfma_f32_16x16x32_bf16 v[88:91], v[160:163], v[206:209], v[88:91]
	v_mfma_f32_16x16x32_bf16 v[76:79], v[142:145], v[214:217], v[76:79]
	v_mfma_f32_16x16x32_bf16 v[72:75], v[160:163], v[214:217], v[72:75]
	v_mfma_f32_16x16x32_bf16 v[124:127], v[156:159], v[188:191], v[124:127]
	v_mfma_f32_16x16x32_bf16 v[120:123], v[164:167], v[188:191], v[120:123]
	v_mfma_f32_16x16x32_bf16 v[108:111], v[156:159], v[202:205], v[108:111]
	v_mfma_f32_16x16x32_bf16 v[104:107], v[164:167], v[202:205], v[104:107]
	v_mfma_f32_16x16x32_bf16 v[92:95], v[156:159], v[210:213], v[92:95]
	v_mfma_f32_16x16x32_bf16 v[88:91], v[164:167], v[210:213], v[88:91]
	v_mfma_f32_16x16x32_bf16 v[76:79], v[156:159], v[228:231], v[76:79]
	v_mfma_f32_16x16x32_bf16 v[72:75], v[164:167], v[228:231], v[72:75]
	s_setprio 0
	s_setprio 1
	v_mfma_f32_16x16x32_bf16 v[116:119], v[168:171], v[184:187], v[116:119]
	v_mfma_f32_16x16x32_bf16 v[112:115], v[176:179], v[184:187], v[112:115]
	v_mfma_f32_16x16x32_bf16 v[100:103], v[168:171], v[198:201], v[100:103]
	v_mfma_f32_16x16x32_bf16 v[96:99], v[176:179], v[198:201], v[96:99]
	v_mfma_f32_16x16x32_bf16 v[84:87], v[168:171], v[206:209], v[84:87]
	v_mfma_f32_16x16x32_bf16 v[80:83], v[176:179], v[206:209], v[80:83]
	v_mfma_f32_16x16x32_bf16 v[68:71], v[168:171], v[214:217], v[68:71]
	v_mfma_f32_16x16x32_bf16 v[64:67], v[176:179], v[214:217], v[64:67]
	v_mfma_f32_16x16x32_bf16 v[116:119], v[172:175], v[188:191], v[116:119]
	v_mfma_f32_16x16x32_bf16 v[112:115], v[180:183], v[188:191], v[112:115]
	v_mfma_f32_16x16x32_bf16 v[100:103], v[172:175], v[202:205], v[100:103]
	v_mfma_f32_16x16x32_bf16 v[96:99], v[180:183], v[202:205], v[96:99]
	v_mfma_f32_16x16x32_bf16 v[84:87], v[172:175], v[210:213], v[84:87]
	v_mfma_f32_16x16x32_bf16 v[80:83], v[180:183], v[210:213], v[80:83]
	v_mfma_f32_16x16x32_bf16 v[68:71], v[172:175], v[228:231], v[68:71]
	v_mfma_f32_16x16x32_bf16 v[64:67], v[180:183], v[228:231], v[64:67]
	s_setprio 0
	s_barrier
	ds_read_b128 v[184:187], v155 offset:49152
	ds_read_b128 v[188:191], v155 offset:50176
	ds_read_b128 v[198:201], v155 offset:51200
	ds_read_b128 v[202:205], v155 offset:52224
	ds_read_b128 v[206:209], v155 offset:53248
	ds_read_b128 v[210:213], v155 offset:54272
	ds_read_b128 v[214:217], v155 offset:55296
	ds_read_b128 v[228:231], v155 offset:56320
	s_add_i32 s14, s91, s7
	s_mov_b32 m0, s14
	s_nop 0
	global_load_lds_dwordx4 v196, s[98:99]
	s_add_i32 m0, s14, 0x2000
	s_add_u32 s12, s12, 0x100080
	s_addc_u32 s13, s13, 0
	s_add_i32 s14, s58, s7
	global_load_lds_dwordx4 v132, s[98:99]
	s_mov_b32 m0, s14
	s_nop 0
	global_load_lds_dwordx4 v196, s[12:13]
	s_add_i32 m0, s14, 0x2000
	s_nop 0
	global_load_lds_dwordx4 v132, s[12:13]
	s_waitcnt vmcnt(6)
	s_waitcnt lgkmcnt(0)
	s_barrier
	s_setprio 1
	s_waitcnt lgkmcnt(0)
	v_mfma_f32_16x16x32_bf16 v[60:63], v[142:145], v[184:187], v[60:63]
	v_mfma_f32_16x16x32_bf16 v[56:59], v[160:163], v[184:187], v[56:59]
	v_mfma_f32_16x16x32_bf16 v[44:47], v[142:145], v[198:201], v[44:47]
	v_mfma_f32_16x16x32_bf16 v[40:43], v[160:163], v[198:201], v[40:43]
	v_mfma_f32_16x16x32_bf16 v[28:31], v[142:145], v[206:209], v[28:31]
	v_mfma_f32_16x16x32_bf16 v[24:27], v[160:163], v[206:209], v[24:27]
	v_mfma_f32_16x16x32_bf16 v[12:15], v[142:145], v[214:217], v[12:15]
	v_mfma_f32_16x16x32_bf16 v[8:11], v[160:163], v[214:217], v[8:11]
	v_mfma_f32_16x16x32_bf16 v[60:63], v[156:159], v[188:191], v[60:63]
	v_mfma_f32_16x16x32_bf16 v[56:59], v[164:167], v[188:191], v[56:59]
	v_mfma_f32_16x16x32_bf16 v[44:47], v[156:159], v[202:205], v[44:47]
	v_mfma_f32_16x16x32_bf16 v[40:43], v[164:167], v[202:205], v[40:43]
	v_mfma_f32_16x16x32_bf16 v[28:31], v[156:159], v[210:213], v[28:31]
	v_mfma_f32_16x16x32_bf16 v[24:27], v[164:167], v[210:213], v[24:27]
	v_mfma_f32_16x16x32_bf16 v[12:15], v[156:159], v[228:231], v[12:15]
	v_mfma_f32_16x16x32_bf16 v[8:11], v[164:167], v[228:231], v[8:11]
	s_setprio 0
	s_setprio 1
	v_mfma_f32_16x16x32_bf16 v[52:55], v[168:171], v[184:187], v[52:55]
	v_mfma_f32_16x16x32_bf16 v[48:51], v[176:179], v[184:187], v[48:51]
	v_mfma_f32_16x16x32_bf16 v[36:39], v[168:171], v[198:201], v[36:39]
	v_mfma_f32_16x16x32_bf16 v[32:35], v[176:179], v[198:201], v[32:35]
	v_mfma_f32_16x16x32_bf16 v[20:23], v[168:171], v[206:209], v[20:23]
	v_mfma_f32_16x16x32_bf16 v[16:19], v[176:179], v[206:209], v[16:19]
	v_mfma_f32_16x16x32_bf16 v[4:7], v[168:171], v[214:217], v[4:7]
	v_mfma_f32_16x16x32_bf16 v[0:3], v[176:179], v[214:217], v[0:3]
	v_mfma_f32_16x16x32_bf16 v[52:55], v[172:175], v[188:191], v[52:55]
	v_mfma_f32_16x16x32_bf16 v[48:51], v[180:183], v[188:191], v[48:51]
	v_mfma_f32_16x16x32_bf16 v[36:39], v[172:175], v[202:205], v[36:39]
	v_mfma_f32_16x16x32_bf16 v[32:35], v[180:183], v[202:205], v[32:35]
	v_mfma_f32_16x16x32_bf16 v[20:23], v[172:175], v[210:213], v[20:23]
	v_mfma_f32_16x16x32_bf16 v[16:19], v[180:183], v[210:213], v[16:19]
	v_mfma_f32_16x16x32_bf16 v[4:7], v[172:175], v[228:231], v[4:7]
	v_mfma_f32_16x16x32_bf16 v[0:3], v[180:183], v[228:231], v[0:3]
	s_setprio 0
	s_barrier
	s_add_i32 s42, s42, 2
	s_add_u32 s10, s10, 0x100
	s_addc_u32 s11, s11, 0
	s_add_u32 s25, s25, 0x100
	s_addc_u32 s41, s41, 0
	s_cmp_gt_u32 s42, 61
	s_cbranch_scc0 .LBB0_424
	s_and_b64 vcc, exec, s[20:21]
	s_cbranch_vccz .LBB0_427
	s_barrier

; #define PG8_STAGE(bufoff, gbase, voff) do { _Pragma("unroll") for (int _i = 0; _i < 2; ++_i) \
;         __builtin_amdgcn_global_load_lds((const unsigned*)((const char*)(gbase) + (voff)[_i]), (LAS unsigned*)(lds + (bufoff) + ldsw + _i * 8192), 16, 0, 0); } while (0)
; #define PG8_LDA(dst, b, h) do { _Pragma("unroll") for (int m = 0; m < 4; ++m) _Pragma("unroll") for (int k = 0; k < 2; ++k) dst[m][k] = *(const LAS bf16x8*)(lds + PG8_SA(b, h) + aoff + m * 2048 + k * 1024); } while (0)
; #define PG8_LDB(dst, b, h) do { _Pragma("unroll") for (int n = 0; n < 2; ++n) _Pragma("unroll") for (int k = 0; k < 2; ++k) dst[n][k] = *(const LAS bf16x8*)(lds + PG8_SB(b, h) + boff + n * 2048 + k * 1024); } while (0)
; #define PG8_MMA(ai, bj, At, Bt) do { __builtin_amdgcn_s_setprio(1); _Pragma("unroll") for (int m = 0; m < 4; ++m) _Pragma("unroll") for (int n = 0; n < 2; ++n) _Pragma("unroll") for (int k = 0; k < 2; ++k) \
;         acc[ai][bj][m][n] = __builtin_amdgcn_mfma_f32_16x16x32_bf16(Bt[n][k], At[m][k], acc[ai][bj][m][n], 0, 0, 0); __builtin_amdgcn_s_setprio(0); } while (0)
; #define PG8_WAIT_V(n) asm volatile("s_waitcnt vmcnt(" #n ")" ::: "memory")
; #define PG8_WAIT_L(n) asm volatile("s_waitcnt lgkmcnt(" #n ")" ::: "memory")
; #define PG8_BAR __builtin_amdgcn_s_barrier()
; #define PG8_SCHED __builtin_amdgcn_sched_barrier(0)
; template <class Epi, class Sched, bool ALIGN_EPI = false, bool SP2 = false>
; __device__ __forceinline__ void gemm_phase(LAS unsigned char* lds, const Gemm g, const Sched& S, const Epi& E) {
;     ...
;             const char* a1 = cA + (size_t)(t + 1) * kstep;
;             const char* a2 = last ? nA : cA + (size_t)(t + 2) * kstep; const char* b2 = last ? nB : cB + (size_t)(t + 2) * kstep;
;             const char* a3 = a2 + kstep; const char* b3 = b2 + kstep;
;             if (last && has_next) S.a_ready(nxt);
;             if constexpr (SP2) {
;             PG8_LDB(B0, 0, 0); PG8_LDB(B1, 0, 1); PG8_SCHED; PG8_LDA(At, 0, 0); PG8_STAGE(PG8_SA(1, 1), a1 + hstep, voffA);
;             PG8_WAIT_V(8); PG8_WAIT_L(0); PG8_BAR; PG8_MMA(0, 0, At, B0); PG8_MMA(0, 1, At, B1); PG8_BAR; PG8_SCHED;
;             PG8_LDA(At, 0, 1); PG8_STAGE(PG8_SB(0, 0), b2, voffB); PG8_STAGE(PG8_SB(0, 1), b2 + hstep, voffB); PG8_STAGE(PG8_SA(0, 0), a2, voffA);
;             PG8_WAIT_V(8); PG8_WAIT_L(0); PG8_BAR; PG8_MMA(1, 0, At, B0); PG8_MMA(1, 1, At, B1); PG8_BAR; PG8_SCHED;
.LBB0_510:
	v_add_u32_e32 v138, s48, v141
	ds_read_b128 v[144:147], v138
	ds_read_b128 v[148:151], v138 offset:1024
	ds_read_b128 v[152:155], v138 offset:2048
	ds_read_b128 v[156:159], v138 offset:3072
	v_add_u32_e32 v138, s90, v141
	ds_read_b128 v[160:163], v138
	ds_read_b128 v[164:167], v138 offset:1024
	ds_read_b128 v[168:171], v138 offset:2048
	ds_read_b128 v[172:175], v138 offset:3072
	ds_read_b128 v[176:179], v143
	ds_read_b128 v[180:183], v143 offset:1024
	ds_read_b128 v[184:187], v143 offset:2048
	ds_read_b128 v[188:191], v143 offset:3072
	ds_read_b128 v[198:201], v143 offset:4096
	ds_read_b128 v[202:205], v143 offset:5120
	ds_read_b128 v[206:209], v143 offset:6144
	ds_read_b128 v[210:213], v143 offset:7168
	s_add_u32 s100, s24, 0xfff00000
	s_addc_u32 s101, s25, -1
	s_add_u32 s26, s24, 0xfff00080
	s_addc_u32 s27, s25, -1
	s_cmp_eq_u32 s41, 60
	s_cselect_b32 s29, s19, s27
	s_cselect_b32 s28, s37, s26
	s_cselect_b32 s27, s15, s40
	s_cselect_b32 s26, s38, s39
	s_add_i32 m0, s3, 0xc000
	s_mov_b32 m0, s30
	s_nop 0
	global_load_lds_dwordx4 v132, s[100:101]
	s_mov_b32 m0, s31
	s_nop 0
	global_load_lds_dwordx4 v130, s[100:101]
	s_add_i32 m0, s3, 0xc000
	s_nop 0
	global_load_lds_dwordx4 v134, s[24:25]
	s_add_i32 m0, s3, 0xe000
	s_nop 0
	global_load_lds_dwordx4 v136, s[24:25]
	s_waitcnt vmcnt(8)
	s_waitcnt lgkmcnt(0)
	s_barrier
	s_setprio 1
	s_waitcnt lgkmcnt(0)
	v_mfma_f32_16x16x32_bf16 v[124:127], v[144:147], v[176:179], v[124:127]
	v_mfma_f32_16x16x32_bf16 v[120:123], v[152:155], v[176:179], v[120:123]
	v_mfma_f32_16x16x32_bf16 v[116:119], v[144:147], v[184:187], v[116:119]
	v_mfma_f32_16x16x32_bf16 v[108:111], v[152:155], v[184:187], v[108:111]
	v_mfma_f32_16x16x32_bf16 v[100:103], v[144:147], v[198:201], v[100:103]
	v_mfma_f32_16x16x32_bf16 v[92:95], v[152:155], v[198:201], v[92:95]
	v_mfma_f32_16x16x32_bf16 v[80:83], v[144:147], v[206:209], v[80:83]
	v_mfma_f32_16x16x32_bf16 v[72:75], v[152:155], v[206:209], v[72:75]
	v_mfma_f32_16x16x32_bf16 v[124:127], v[148:151], v[180:183], v[124:127]
	v_mfma_f32_16x16x32_bf16 v[120:123], v[156:159], v[180:183], v[120:123]
	v_mfma_f32_16x16x32_bf16 v[116:119], v[148:151], v[188:191], v[116:119]
	v_mfma_f32_16x16x32_bf16 v[108:111], v[156:159], v[188:191], v[108:111]
	v_mfma_f32_16x16x32_bf16 v[100:103], v[148:151], v[202:205], v[100:103]
	v_mfma_f32_16x16x32_bf16 v[92:95], v[156:159], v[202:205], v[92:95]
	v_mfma_f32_16x16x32_bf16 v[80:83], v[148:151], v[210:213], v[80:83]
	v_mfma_f32_16x16x32_bf16 v[72:75], v[156:159], v[210:213], v[72:75]
	s_setprio 0
	s_setprio 1
	v_mfma_f32_16x16x32_bf16 v[112:115], v[160:163], v[176:179], v[112:115]
	v_mfma_f32_16x16x32_bf16 v[104:107], v[168:171], v[176:179], v[104:107]
	v_mfma_f32_16x16x32_bf16 v[96:99], v[160:163], v[184:187], v[96:99]
	v_mfma_f32_16x16x32_bf16 v[88:91], v[168:171], v[184:187], v[88:91]
	v_mfma_f32_16x16x32_bf16 v[84:87], v[160:163], v[198:201], v[84:87]
	v_mfma_f32_16x16x32_bf16 v[76:79], v[168:171], v[198:201], v[76:79]
	v_mfma_f32_16x16x32_bf16 v[68:71], v[160:163], v[206:209], v[68:71]
	v_mfma_f32_16x16x32_bf16 v[64:67], v[168:171], v[206:209], v[64:67]
	v_mfma_f32_16x16x32_bf16 v[112:115], v[164:167], v[180:183], v[112:115]
	v_mfma_f32_16x16x32_bf16 v[104:107], v[172:175], v[180:183], v[104:107]
	v_mfma_f32_16x16x32_bf16 v[96:99], v[164:167], v[188:191], v[96:99]
	v_mfma_f32_16x16x32_bf16 v[88:91], v[172:175], v[188:191], v[88:91]
	v_mfma_f32_16x16x32_bf16 v[84:87], v[164:167], v[202:205], v[84:87]
	v_mfma_f32_16x16x32_bf16 v[76:79], v[172:175], v[202:205], v[76:79]
	v_mfma_f32_16x16x32_bf16 v[68:71], v[164:167], v[210:213], v[68:71]
	v_mfma_f32_16x16x32_bf16 v[64:67], v[172:175], v[210:213], v[64:67]
	s_setprio 0
	s_barrier
	ds_read_b128 v[176:179], v143 offset:16384
	ds_read_b128 v[180:183], v143 offset:17408
	ds_read_b128 v[184:187], v143 offset:18432
	ds_read_b128 v[188:191], v143 offset:19456
	ds_read_b128 v[198:201], v143 offset:20480
	ds_read_b128 v[202:205], v143 offset:21504
	ds_read_b128 v[206:209], v143 offset:22528
	ds_read_b128 v[210:213], v143 offset:23552
	s_add_u32 s98, s26, 0x80
	s_addc_u32 s99, s27, 0
	s_add_i32 s42, s48, s2
	s_mov_b32 m0, s42
	s_nop 0
	global_load_lds_dwordx4 v196, s[26:27]
	s_add_i32 m0, s42, 0x2000
	s_add_u32 s46, s26, 0x100000
	s_addc_u32 s47, s27, 0
	s_add_i32 s42, s90, s2
	global_load_lds_dwordx4 v128, s[26:27]
	s_mov_b32 m0, s42
	s_nop 0
	global_load_lds_dwordx4 v196, s[46:47]
	s_add_i32 m0, s42, 0x2000
	s_nop 0
	global_load_lds_dwordx4 v128, s[46:47]
	s_waitcnt vmcnt(6)
	s_waitcnt lgkmcnt(0)
	s_barrier
; #define PG8_STAGE(bufoff, gbase, voff) do { _Pragma("unroll") for (int _i = 0; _i < 2; ++_i) \
;         __builtin_amdgcn_global_load_lds((const unsigned*)((const char*)(gbase) + (voff)[_i]), (LAS unsigned*)(lds + (bufoff) + ldsw + _i * 8192), 16, 0, 0); } while (0)
; #define PG8_LDA(dst, b, h) do { _Pragma("unroll") for (int m = 0; m < 4; ++m) _Pragma("unroll") for (int k = 0; k < 2; ++k) dst[m][k] = *(const LAS bf16x8*)(lds + PG8_SA(b, h) + aoff + m * 2048 + k * 1024); } while (0)
; #define PG8_LDB(dst, b, h) do { _Pragma("unroll") for (int n = 0; n < 2; ++n) _Pragma("unroll") for (int k = 0; k < 2; ++k) dst[n][k] = *(const LAS bf16x8*)(lds + PG8_SB(b, h) + boff + n * 2048 + k * 1024); } while (0)
; #define PG8_MMA(ai, bj, At, Bt) do { __builtin_amdgcn_s_setprio(1); _Pragma("unroll") for (int m = 0; m < 4; ++m) _Pragma("unroll") for (int n = 0; n < 2; ++n) _Pragma("unroll") for (int k = 0; k < 2; ++k) \
;         acc[ai][bj][m][n] = __builtin_amdgcn_mfma_f32_16x16x32_bf16(Bt[n][k], At[m][k], acc[ai][bj][m][n], 0, 0, 0); __builtin_amdgcn_s_setprio(0); } while (0)
; #define PG8_WAIT_V(n) asm volatile("s_waitcnt vmcnt(" #n ")" ::: "memory")
; #define PG8_WAIT_L(n) asm volatile("s_waitcnt lgkmcnt(" #n ")" ::: "memory")
; #define PG8_BAR __builtin_amdgcn_s_barrier()
; #define PG8_SCHED __builtin_amdgcn_sched_barrier(0)
; template <class Epi, class Sched, bool ALIGN_EPI = false, bool SP2 = false>
; __device__ __forceinline__ void gemm_phase(LAS unsigned char* lds, const Gemm g, const Sched& S, const Epi& E) {
;     ...
;             PG8_LDA(At, 0, 1); PG8_STAGE(PG8_SB(0, 0), b2, voffB); PG8_STAGE(PG8_SB(0, 1), b2 + hstep, voffB); PG8_STAGE(PG8_SA(0, 0), a2, voffA);
;             PG8_WAIT_V(8); PG8_WAIT_L(0); PG8_BAR; PG8_MMA(1, 0, At, B0); PG8_MMA(1, 1, At, B1); PG8_BAR; PG8_SCHED;
;             PG8_LDB(B0, 1, 0); PG8_LDB(B1, 1, 1); PG8_SCHED; PG8_LDA(At, 1, 0); PG8_STAGE(PG8_SA(0, 1), a2 + hstep, voffA);
;             PG8_WAIT_V(8); PG8_WAIT_L(0); PG8_BAR; PG8_MMA(0, 0, At, B0); PG8_MMA(0, 1, At, B1); PG8_BAR; PG8_SCHED;
	s_setprio 1
	s_waitcnt lgkmcnt(0)
	v_mfma_f32_16x16x32_bf16 v[60:63], v[144:147], v[176:179], v[60:63]
	v_mfma_f32_16x16x32_bf16 v[56:59], v[152:155], v[176:179], v[56:59]
	v_mfma_f32_16x16x32_bf16 v[52:55], v[144:147], v[184:187], v[52:55]
	v_mfma_f32_16x16x32_bf16 v[44:47], v[152:155], v[184:187], v[44:47]
	v_mfma_f32_16x16x32_bf16 v[36:39], v[144:147], v[198:201], v[36:39]
	v_mfma_f32_16x16x32_bf16 v[28:31], v[152:155], v[198:201], v[28:31]
	v_mfma_f32_16x16x32_bf16 v[20:23], v[144:147], v[206:209], v[20:23]
	v_mfma_f32_16x16x32_bf16 v[12:15], v[152:155], v[206:209], v[12:15]
	v_mfma_f32_16x16x32_bf16 v[60:63], v[148:151], v[180:183], v[60:63]
	v_mfma_f32_16x16x32_bf16 v[56:59], v[156:159], v[180:183], v[56:59]
	v_mfma_f32_16x16x32_bf16 v[52:55], v[148:151], v[188:191], v[52:55]
	v_mfma_f32_16x16x32_bf16 v[44:47], v[156:159], v[188:191], v[44:47]
	v_mfma_f32_16x16x32_bf16 v[36:39], v[148:151], v[202:205], v[36:39]
	v_mfma_f32_16x16x32_bf16 v[28:31], v[156:159], v[202:205], v[28:31]
	v_mfma_f32_16x16x32_bf16 v[20:23], v[148:151], v[210:213], v[20:23]
	v_mfma_f32_16x16x32_bf16 v[12:15], v[156:159], v[210:213], v[12:15]
	s_setprio 0
	s_setprio 1
	v_mfma_f32_16x16x32_bf16 v[48:51], v[160:163], v[176:179], v[48:51]
	v_mfma_f32_16x16x32_bf16 v[40:43], v[168:171], v[176:179], v[40:43]
	v_mfma_f32_16x16x32_bf16 v[32:35], v[160:163], v[184:187], v[32:35]
	v_mfma_f32_16x16x32_bf16 v[24:27], v[168:171], v[184:187], v[24:27]
	v_mfma_f32_16x16x32_bf16 v[16:19], v[160:163], v[198:201], v[16:19]
	v_mfma_f32_16x16x32_bf16 v[8:11], v[168:171], v[198:201], v[8:11]
	v_mfma_f32_16x16x32_bf16 v[4:7], v[160:163], v[206:209], v[4:7]
	v_mfma_f32_16x16x32_bf16 v[0:3], v[168:171], v[206:209], v[0:3]
	v_mfma_f32_16x16x32_bf16 v[48:51], v[164:167], v[180:183], v[48:51]
	v_mfma_f32_16x16x32_bf16 v[40:43], v[172:175], v[180:183], v[40:43]
	v_mfma_f32_16x16x32_bf16 v[32:35], v[164:167], v[188:191], v[32:35]
	v_mfma_f32_16x16x32_bf16 v[24:27], v[172:175], v[188:191], v[24:27]
	v_mfma_f32_16x16x32_bf16 v[16:19], v[164:167], v[202:205], v[16:19]
	v_mfma_f32_16x16x32_bf16 v[8:11], v[172:175], v[202:205], v[8:11]
	v_mfma_f32_16x16x32_bf16 v[4:7], v[164:167], v[210:213], v[4:7]
	v_mfma_f32_16x16x32_bf16 v[0:3], v[172:175], v[210:213], v[0:3]
	s_setprio 0
	s_barrier
	v_add_u32_e32 v156, s91, v141
	v_add_u32_e32 v172, s58, v141
	ds_read_b128 v[144:147], v156
	ds_read_b128 v[148:151], v156 offset:1024
	ds_read_b128 v[152:155], v156 offset:2048
	ds_read_b128 v[156:159], v156 offset:3072
	ds_read_b128 v[160:163], v172
	ds_read_b128 v[164:167], v172 offset:1024
	ds_read_b128 v[168:171], v172 offset:2048
	ds_read_b128 v[172:175], v172 offset:3072
	ds_read_b128 v[176:179], v143 offset:32768
	ds_read_b128 v[180:183], v143 offset:33792
	ds_read_b128 v[184:187], v143 offset:34816
	ds_read_b128 v[188:191], v143 offset:35840
	ds_read_b128 v[198:201], v143 offset:36864
	ds_read_b128 v[202:205], v143 offset:37888
	ds_read_b128 v[206:209], v143 offset:38912
	ds_read_b128 v[210:213], v143 offset:39936
	s_mov_b32 m0, s3
	s_nop 0
	global_load_lds_dwordx4 v132, s[28:29]
	s_mov_b32 m0, s6
	s_nop 0
	global_load_lds_dwordx4 v130, s[28:29]
	s_add_u32 s28, s28, 0x100000
	s_addc_u32 s29, s29, 0
	s_mov_b32 m0, s7
	s_nop 0
	global_load_lds_dwordx4 v132, s[28:29]
	s_mov_b32 m0, s17
	s_nop 0
	global_load_lds_dwordx4 v130, s[28:29]
	s_waitcnt vmcnt(8)
	s_waitcnt lgkmcnt(0)
	s_barrier
; #define PG8_STAGE(bufoff, gbase, voff) do { _Pragma("unroll") for (int _i = 0; _i < 2; ++_i) \
;         __builtin_amdgcn_global_load_lds((const unsigned*)((const char*)(gbase) + (voff)[_i]), (LAS unsigned*)(lds + (bufoff) + ldsw + _i * 8192), 16, 0, 0); } while (0)
; #define PG8_LDA(dst, b, h) do { _Pragma("unroll") for (int m = 0; m < 4; ++m) _Pragma("unroll") for (int k = 0; k < 2; ++k) dst[m][k] = *(const LAS bf16x8*)(lds + PG8_SA(b, h) + aoff + m * 2048 + k * 1024); } while (0)
; #define PG8_MMA(ai, bj, At, Bt) do { __builtin_amdgcn_s_setprio(1); _Pragma("unroll") for (int m = 0; m < 4; ++m) _Pragma("unroll") for (int n = 0; n < 2; ++n) _Pragma("unroll") for (int k = 0; k < 2; ++k) \
;         acc[ai][bj][m][n] = __builtin_amdgcn_mfma_f32_16x16x32_bf16(Bt[n][k], At[m][k], acc[ai][bj][m][n], 0, 0, 0); __builtin_amdgcn_s_setprio(0); } while (0)
; #define PG8_WAIT_V(n) asm volatile("s_waitcnt vmcnt(" #n ")" ::: "memory")
; #define PG8_WAIT_L(n) asm volatile("s_waitcnt lgkmcnt(" #n ")" ::: "memory")
; #define PG8_BAR __builtin_amdgcn_s_barrier()
; #define PG8_SCHED __builtin_amdgcn_sched_barrier(0)
; template <class Epi, class Sched, bool ALIGN_EPI = false, bool SP2 = false>
; __device__ __forceinline__ void gemm_phase(LAS unsigned char* lds, const Gemm g, const Sched& S, const Epi& E) {
;     ...
;             PG8_WAIT_V(8); PG8_WAIT_L(0); PG8_BAR; PG8_MMA(0, 0, At, B0); PG8_MMA(0, 1, At, B1); PG8_BAR; PG8_SCHED;
;             PG8_LDA(At, 1, 1); PG8_STAGE(PG8_SB(1, 0), b3, voffB); PG8_STAGE(PG8_SB(1, 1), b3 + hstep, voffB); PG8_STAGE(PG8_SA(1, 0), a3, voffA);
;             PG8_WAIT_V(8); PG8_WAIT_L(0); PG8_BAR; PG8_MMA(1, 0, At, B0); PG8_MMA(1, 1, At, B1); PG8_BAR; PG8_SCHED;
;     ...
;         if constexpr (ALIGN_EPI) { if (wr == 0) PG8_BAR; }
	s_setprio 1
	s_waitcnt lgkmcnt(0)
	v_mfma_f32_16x16x32_bf16 v[124:127], v[144:147], v[176:179], v[124:127]
	v_mfma_f32_16x16x32_bf16 v[120:123], v[152:155], v[176:179], v[120:123]
	v_mfma_f32_16x16x32_bf16 v[116:119], v[144:147], v[184:187], v[116:119]
	v_mfma_f32_16x16x32_bf16 v[108:111], v[152:155], v[184:187], v[108:111]
	v_mfma_f32_16x16x32_bf16 v[100:103], v[144:147], v[198:201], v[100:103]
	v_mfma_f32_16x16x32_bf16 v[92:95], v[152:155], v[198:201], v[92:95]
	v_mfma_f32_16x16x32_bf16 v[80:83], v[144:147], v[206:209], v[80:83]
	v_mfma_f32_16x16x32_bf16 v[72:75], v[152:155], v[206:209], v[72:75]
	v_mfma_f32_16x16x32_bf16 v[124:127], v[148:151], v[180:183], v[124:127]
	v_mfma_f32_16x16x32_bf16 v[120:123], v[156:159], v[180:183], v[120:123]
	v_mfma_f32_16x16x32_bf16 v[116:119], v[148:151], v[188:191], v[116:119]
	v_mfma_f32_16x16x32_bf16 v[108:111], v[156:159], v[188:191], v[108:111]
	v_mfma_f32_16x16x32_bf16 v[100:103], v[148:151], v[202:205], v[100:103]
	v_mfma_f32_16x16x32_bf16 v[92:95], v[156:159], v[202:205], v[92:95]
	v_mfma_f32_16x16x32_bf16 v[80:83], v[148:151], v[210:213], v[80:83]
	v_mfma_f32_16x16x32_bf16 v[72:75], v[156:159], v[210:213], v[72:75]
	s_setprio 0
	s_setprio 1
	v_mfma_f32_16x16x32_bf16 v[112:115], v[160:163], v[176:179], v[112:115]
	v_mfma_f32_16x16x32_bf16 v[104:107], v[168:171], v[176:179], v[104:107]
	v_mfma_f32_16x16x32_bf16 v[96:99], v[160:163], v[184:187], v[96:99]
	v_mfma_f32_16x16x32_bf16 v[88:91], v[168:171], v[184:187], v[88:91]
	v_mfma_f32_16x16x32_bf16 v[84:87], v[160:163], v[198:201], v[84:87]
	v_mfma_f32_16x16x32_bf16 v[76:79], v[168:171], v[198:201], v[76:79]
	v_mfma_f32_16x16x32_bf16 v[68:71], v[160:163], v[206:209], v[68:71]
	v_mfma_f32_16x16x32_bf16 v[64:67], v[168:171], v[206:209], v[64:67]
	v_mfma_f32_16x16x32_bf16 v[112:115], v[164:167], v[180:183], v[112:115]
	v_mfma_f32_16x16x32_bf16 v[104:107], v[172:175], v[180:183], v[104:107]
	v_mfma_f32_16x16x32_bf16 v[96:99], v[164:167], v[188:191], v[96:99]
	v_mfma_f32_16x16x32_bf16 v[88:91], v[172:175], v[188:191], v[88:91]
	v_mfma_f32_16x16x32_bf16 v[84:87], v[164:167], v[202:205], v[84:87]
	v_mfma_f32_16x16x32_bf16 v[76:79], v[172:175], v[202:205], v[76:79]
	v_mfma_f32_16x16x32_bf16 v[68:71], v[164:167], v[210:213], v[68:71]
	v_mfma_f32_16x16x32_bf16 v[64:67], v[172:175], v[210:213], v[64:67]
	s_setprio 0
	s_barrier
	ds_read_b128 v[176:179], v143 offset:49152
	ds_read_b128 v[180:183], v143 offset:50176
	ds_read_b128 v[184:187], v143 offset:51200
	ds_read_b128 v[188:191], v143 offset:52224
	ds_read_b128 v[198:201], v143 offset:53248
	ds_read_b128 v[202:205], v143 offset:54272
	ds_read_b128 v[206:209], v143 offset:55296
	ds_read_b128 v[210:213], v143 offset:56320
	s_add_i32 s28, s91, s2
	s_mov_b32 m0, s28
	s_nop 0
	global_load_lds_dwordx4 v196, s[98:99]
	s_add_i32 m0, s28, 0x2000
	s_add_u32 s26, s26, 0x100080
	s_addc_u32 s27, s27, 0
	s_add_i32 s28, s58, s2
	global_load_lds_dwordx4 v128, s[98:99]
	s_mov_b32 m0, s28
	s_nop 0
	global_load_lds_dwordx4 v196, s[26:27]
	s_add_i32 m0, s28, 0x2000
	s_nop 0
	global_load_lds_dwordx4 v128, s[26:27]
	s_waitcnt vmcnt(6)
	s_waitcnt lgkmcnt(0)
	s_barrier
	s_setprio 1
	s_waitcnt lgkmcnt(0)
	v_mfma_f32_16x16x32_bf16 v[60:63], v[144:147], v[176:179], v[60:63]
	v_mfma_f32_16x16x32_bf16 v[56:59], v[152:155], v[176:179], v[56:59]
	v_mfma_f32_16x16x32_bf16 v[52:55], v[144:147], v[184:187], v[52:55]
	v_mfma_f32_16x16x32_bf16 v[44:47], v[152:155], v[184:187], v[44:47]
	v_mfma_f32_16x16x32_bf16 v[36:39], v[144:147], v[198:201], v[36:39]
	v_mfma_f32_16x16x32_bf16 v[28:31], v[152:155], v[198:201], v[28:31]
	v_mfma_f32_16x16x32_bf16 v[20:23], v[144:147], v[206:209], v[20:23]
	v_mfma_f32_16x16x32_bf16 v[12:15], v[152:155], v[206:209], v[12:15]
	v_mfma_f32_16x16x32_bf16 v[60:63], v[148:151], v[180:183], v[60:63]
	v_mfma_f32_16x16x32_bf16 v[56:59], v[156:159], v[180:183], v[56:59]
	v_mfma_f32_16x16x32_bf16 v[52:55], v[148:151], v[188:191], v[52:55]
	v_mfma_f32_16x16x32_bf16 v[44:47], v[156:159], v[188:191], v[44:47]
	v_mfma_f32_16x16x32_bf16 v[36:39], v[148:151], v[202:205], v[36:39]
	v_mfma_f32_16x16x32_bf16 v[28:31], v[156:159], v[202:205], v[28:31]
	v_mfma_f32_16x16x32_bf16 v[20:23], v[148:151], v[210:213], v[20:23]
	v_mfma_f32_16x16x32_bf16 v[12:15], v[156:159], v[210:213], v[12:15]
	s_setprio 0
	s_setprio 1
	v_mfma_f32_16x16x32_bf16 v[48:51], v[160:163], v[176:179], v[48:51]
	v_mfma_f32_16x16x32_bf16 v[40:43], v[168:171], v[176:179], v[40:43]
	v_mfma_f32_16x16x32_bf16 v[32:35], v[160:163], v[184:187], v[32:35]
	v_mfma_f32_16x16x32_bf16 v[24:27], v[168:171], v[184:187], v[24:27]
	v_mfma_f32_16x16x32_bf16 v[16:19], v[160:163], v[198:201], v[16:19]
	v_mfma_f32_16x16x32_bf16 v[8:11], v[168:171], v[198:201], v[8:11]
	v_mfma_f32_16x16x32_bf16 v[4:7], v[160:163], v[206:209], v[4:7]
	v_mfma_f32_16x16x32_bf16 v[0:3], v[168:171], v[206:209], v[0:3]
	v_mfma_f32_16x16x32_bf16 v[48:51], v[164:167], v[180:183], v[48:51]
	v_mfma_f32_16x16x32_bf16 v[40:43], v[172:175], v[180:183], v[40:43]
	v_mfma_f32_16x16x32_bf16 v[32:35], v[164:167], v[188:191], v[32:35]
	v_mfma_f32_16x16x32_bf16 v[24:27], v[172:175], v[188:191], v[24:27]
	v_mfma_f32_16x16x32_bf16 v[16:19], v[164:167], v[202:205], v[16:19]
	v_mfma_f32_16x16x32_bf16 v[8:11], v[172:175], v[202:205], v[8:11]
	v_mfma_f32_16x16x32_bf16 v[4:7], v[164:167], v[210:213], v[4:7]
	v_mfma_f32_16x16x32_bf16 v[0:3], v[172:175], v[210:213], v[0:3]
	s_setprio 0
	s_barrier
	s_add_i32 s41, s41, 2
	s_add_u32 s24, s24, 0x100
	s_addc_u32 s25, s25, 0
	s_add_u32 s39, s39, 0x100
	s_addc_u32 s40, s40, 0
	s_cmp_gt_u32 s41, 61
	s_cbranch_scc0 .LBB0_510
	s_and_b64 vcc, exec, s[10:11]
	s_cbranch_vccz .LBB0_513
	s_barrier

; #define PG8_STAGE(bufoff, gbase, voff) do { _Pragma("unroll") for (int _i = 0; _i < 2; ++_i) \
;         __builtin_amdgcn_global_load_lds((const unsigned*)((const char*)(gbase) + (voff)[_i]), (LAS unsigned*)(lds + (bufoff) + ldsw + _i * 8192), 16, 0, 0); } while (0)
; #define PG8_LDA(dst, b, h) do { _Pragma("unroll") for (int m = 0; m < 4; ++m) _Pragma("unroll") for (int k = 0; k < 2; ++k) dst[m][k] = *(const LAS bf16x8*)(lds + PG8_SA(b, h) + aoff + m * 2048 + k * 1024); } while (0)
; #define PG8_LDB(dst, b, h) do { _Pragma("unroll") for (int n = 0; n < 2; ++n) _Pragma("unroll") for (int k = 0; k < 2; ++k) dst[n][k] = *(const LAS bf16x8*)(lds + PG8_SB(b, h) + boff + n * 2048 + k * 1024); } while (0)
; #define PG8_MMA(ai, bj, At, Bt) do { __builtin_amdgcn_s_setprio(1); _Pragma("unroll") for (int m = 0; m < 4; ++m) _Pragma("unroll") for (int n = 0; n < 2; ++n) _Pragma("unroll") for (int k = 0; k < 2; ++k) \
;         acc[ai][bj][m][n] = __builtin_amdgcn_mfma_f32_16x16x32_bf16(Bt[n][k], At[m][k], acc[ai][bj][m][n], 0, 0, 0); __builtin_amdgcn_s_setprio(0); } while (0)
; #define PG8_WAIT_V(n) asm volatile("s_waitcnt vmcnt(" #n ")" ::: "memory")
; #define PG8_WAIT_L(n) asm volatile("s_waitcnt lgkmcnt(" #n ")" ::: "memory")
; #define PG8_BAR __builtin_amdgcn_s_barrier()
; #define PG8_SCHED __builtin_amdgcn_sched_barrier(0)
; template <class Epi, class Sched, bool ALIGN_EPI = false, bool SP2 = false>
; __device__ __forceinline__ void gemm_phase(LAS unsigned char* lds, const Gemm g, const Sched& S, const Epi& E) {
;     ...
;             const char* a1 = cA + (size_t)(t + 1) * kstep;
;             const char* a2 = last ? nA : cA + (size_t)(t + 2) * kstep; const char* b2 = last ? nB : cB + (size_t)(t + 2) * kstep;
;             const char* a3 = a2 + kstep; const char* b3 = b2 + kstep;
;             if (last && has_next) S.a_ready(nxt);
;             if constexpr (SP2) {
;             PG8_LDB(B0, 0, 0); PG8_LDB(B1, 0, 1); PG8_SCHED; PG8_LDA(At, 0, 0); PG8_STAGE(PG8_SA(1, 1), a1 + hstep, voffA);
;             PG8_WAIT_V(8); PG8_WAIT_L(0); PG8_BAR; PG8_MMA(0, 0, At, B0); PG8_MMA(0, 1, At, B1); PG8_BAR; PG8_SCHED;
;             PG8_LDA(At, 0, 1); PG8_STAGE(PG8_SB(0, 0), b2, voffB); PG8_STAGE(PG8_SB(0, 1), b2 + hstep, voffB); PG8_STAGE(PG8_SA(0, 0), a2, voffA);
;             PG8_WAIT_V(8); PG8_WAIT_L(0); PG8_BAR; PG8_MMA(1, 0, At, B0); PG8_MMA(1, 1, At, B1); PG8_BAR; PG8_SCHED;
.LBB0_832:
	v_add_u32_e32 v150, s48, v157
	v_add_u32_e32 v154, s90, v157
	ds_read_b128 v[128:131], v150
	ds_read_b128 v[132:135], v150 offset:1024
	ds_read_b128 v[146:149], v150 offset:2048
	ds_read_b128 v[150:153], v150 offset:3072
	ds_read_b128 v[160:163], v154
	ds_read_b128 v[164:167], v154 offset:1024
	ds_read_b128 v[168:171], v154 offset:2048
	ds_read_b128 v[172:175], v154 offset:3072
	ds_read_b128 v[176:179], v159
	ds_read_b128 v[180:183], v159 offset:1024
	ds_read_b128 v[184:187], v159 offset:2048
	ds_read_b128 v[188:191], v159 offset:3072
	ds_read_b128 v[198:201], v159 offset:4096
	ds_read_b128 v[202:205], v159 offset:5120
	ds_read_b128 v[206:209], v159 offset:6144
	ds_read_b128 v[210:213], v159 offset:7168
	s_add_u32 s100, s10, 0xfff00000
	s_addc_u32 s101, s11, -1
	s_add_u32 s34, s10, 0xfff00080
	s_addc_u32 s35, s11, -1
	s_cmp_eq_u32 s62, 60
	s_cselect_b32 s37, s27, s35
	s_cselect_b32 s36, s47, s34
	s_cselect_b32 s35, s25, s59
	s_cselect_b32 s34, s49, s54
	s_add_i32 m0, s3, 0xc000
	s_mov_b32 m0, s41
	s_nop 0
	global_load_lds_dwordx4 v140, s[100:101]
	s_mov_b32 m0, s42
	s_nop 0
	global_load_lds_dwordx4 v138, s[100:101]
	s_add_i32 m0, s3, 0xc000
	s_nop 0
	global_load_lds_dwordx4 v142, s[10:11]
	s_add_i32 m0, s3, 0xe000
	s_nop 0
	global_load_lds_dwordx4 v144, s[10:11]
	s_waitcnt vmcnt(8)
	s_waitcnt lgkmcnt(0)
	s_barrier
	s_setprio 1
	s_waitcnt lgkmcnt(0)
	v_mfma_f32_16x16x32_bf16 v[124:127], v[128:131], v[176:179], v[124:127]
	v_mfma_f32_16x16x32_bf16 v[120:123], v[146:149], v[176:179], v[120:123]
	v_mfma_f32_16x16x32_bf16 v[108:111], v[128:131], v[184:187], v[108:111]
	v_mfma_f32_16x16x32_bf16 v[104:107], v[146:149], v[184:187], v[104:107]
	v_mfma_f32_16x16x32_bf16 v[92:95], v[128:131], v[198:201], v[92:95]
	v_mfma_f32_16x16x32_bf16 v[88:91], v[146:149], v[198:201], v[88:91]
	v_mfma_f32_16x16x32_bf16 v[76:79], v[128:131], v[206:209], v[76:79]
	v_mfma_f32_16x16x32_bf16 v[72:75], v[146:149], v[206:209], v[72:75]
	v_mfma_f32_16x16x32_bf16 v[124:127], v[132:135], v[180:183], v[124:127]
	v_mfma_f32_16x16x32_bf16 v[120:123], v[150:153], v[180:183], v[120:123]
	v_mfma_f32_16x16x32_bf16 v[108:111], v[132:135], v[188:191], v[108:111]
	v_mfma_f32_16x16x32_bf16 v[104:107], v[150:153], v[188:191], v[104:107]
	v_mfma_f32_16x16x32_bf16 v[92:95], v[132:135], v[202:205], v[92:95]
	v_mfma_f32_16x16x32_bf16 v[88:91], v[150:153], v[202:205], v[88:91]
	v_mfma_f32_16x16x32_bf16 v[76:79], v[132:135], v[210:213], v[76:79]
	v_mfma_f32_16x16x32_bf16 v[72:75], v[150:153], v[210:213], v[72:75]
	s_setprio 0
	s_setprio 1
	v_mfma_f32_16x16x32_bf16 v[116:119], v[160:163], v[176:179], v[116:119]
	v_mfma_f32_16x16x32_bf16 v[112:115], v[168:171], v[176:179], v[112:115]
	v_mfma_f32_16x16x32_bf16 v[100:103], v[160:163], v[184:187], v[100:103]
	v_mfma_f32_16x16x32_bf16 v[96:99], v[168:171], v[184:187], v[96:99]
	v_mfma_f32_16x16x32_bf16 v[84:87], v[160:163], v[198:201], v[84:87]
	v_mfma_f32_16x16x32_bf16 v[80:83], v[168:171], v[198:201], v[80:83]
	v_mfma_f32_16x16x32_bf16 v[68:71], v[160:163], v[206:209], v[68:71]
	v_mfma_f32_16x16x32_bf16 v[64:67], v[168:171], v[206:209], v[64:67]
	v_mfma_f32_16x16x32_bf16 v[116:119], v[164:167], v[180:183], v[116:119]
	v_mfma_f32_16x16x32_bf16 v[112:115], v[172:175], v[180:183], v[112:115]
	v_mfma_f32_16x16x32_bf16 v[100:103], v[164:167], v[188:191], v[100:103]
	v_mfma_f32_16x16x32_bf16 v[96:99], v[172:175], v[188:191], v[96:99]
	v_mfma_f32_16x16x32_bf16 v[84:87], v[164:167], v[202:205], v[84:87]
	v_mfma_f32_16x16x32_bf16 v[80:83], v[172:175], v[202:205], v[80:83]
	v_mfma_f32_16x16x32_bf16 v[68:71], v[164:167], v[210:213], v[68:71]
	v_mfma_f32_16x16x32_bf16 v[64:67], v[172:175], v[210:213], v[64:67]
	s_setprio 0
	s_barrier
	ds_read_b128 v[176:179], v159 offset:16384
	ds_read_b128 v[180:183], v159 offset:17408
	ds_read_b128 v[184:187], v159 offset:18432
	ds_read_b128 v[188:191], v159 offset:19456
	ds_read_b128 v[198:201], v159 offset:20480
	ds_read_b128 v[202:205], v159 offset:21504
	ds_read_b128 v[206:209], v159 offset:22528
	ds_read_b128 v[210:213], v159 offset:23552
	s_add_u32 s98, s34, 0x80
	s_addc_u32 s99, s35, 0
	s_add_i32 s63, s48, s0
	s_mov_b32 m0, s63
	s_nop 0
	global_load_lds_dwordx4 v196, s[34:35]
	s_add_i32 m0, s63, 0x2000
	s_add_u32 s64, s34, 0x100000
	s_addc_u32 s65, s35, 0
	s_add_i32 s63, s90, s0
	global_load_lds_dwordx4 v136, s[34:35]
	s_mov_b32 m0, s63
	s_nop 0
	global_load_lds_dwordx4 v196, s[64:65]
	s_add_i32 m0, s63, 0x2000
	s_nop 0
	global_load_lds_dwordx4 v136, s[64:65]
	s_waitcnt vmcnt(6)
	s_waitcnt lgkmcnt(0)
	s_barrier
; #define PG8_STAGE(bufoff, gbase, voff) do { _Pragma("unroll") for (int _i = 0; _i < 2; ++_i) \
;         __builtin_amdgcn_global_load_lds((const unsigned*)((const char*)(gbase) + (voff)[_i]), (LAS unsigned*)(lds + (bufoff) + ldsw + _i * 8192), 16, 0, 0); } while (0)
; #define PG8_LDA(dst, b, h) do { _Pragma("unroll") for (int m = 0; m < 4; ++m) _Pragma("unroll") for (int k = 0; k < 2; ++k) dst[m][k] = *(const LAS bf16x8*)(lds + PG8_SA(b, h) + aoff + m * 2048 + k * 1024); } while (0)
; #define PG8_LDB(dst, b, h) do { _Pragma("unroll") for (int n = 0; n < 2; ++n) _Pragma("unroll") for (int k = 0; k < 2; ++k) dst[n][k] = *(const LAS bf16x8*)(lds + PG8_SB(b, h) + boff + n * 2048 + k * 1024); } while (0)
; #define PG8_MMA(ai, bj, At, Bt) do { __builtin_amdgcn_s_setprio(1); _Pragma("unroll") for (int m = 0; m < 4; ++m) _Pragma("unroll") for (int n = 0; n < 2; ++n) _Pragma("unroll") for (int k = 0; k < 2; ++k) \
;         acc[ai][bj][m][n] = __builtin_amdgcn_mfma_f32_16x16x32_bf16(Bt[n][k], At[m][k], acc[ai][bj][m][n], 0, 0, 0); __builtin_amdgcn_s_setprio(0); } while (0)
; #define PG8_WAIT_V(n) asm volatile("s_waitcnt vmcnt(" #n ")" ::: "memory")
; #define PG8_WAIT_L(n) asm volatile("s_waitcnt lgkmcnt(" #n ")" ::: "memory")
; #define PG8_BAR __builtin_amdgcn_s_barrier()
; #define PG8_SCHED __builtin_amdgcn_sched_barrier(0)
; template <class Epi, class Sched, bool ALIGN_EPI = false, bool SP2 = false>
; __device__ __forceinline__ void gemm_phase(LAS unsigned char* lds, const Gemm g, const Sched& S, const Epi& E) {
;     ...
;             PG8_LDA(At, 0, 1); PG8_STAGE(PG8_SB(0, 0), b2, voffB); PG8_STAGE(PG8_SB(0, 1), b2 + hstep, voffB); PG8_STAGE(PG8_SA(0, 0), a2, voffA);
;             PG8_WAIT_V(8); PG8_WAIT_L(0); PG8_BAR; PG8_MMA(1, 0, At, B0); PG8_MMA(1, 1, At, B1); PG8_BAR; PG8_SCHED;
;             PG8_LDB(B0, 1, 0); PG8_LDB(B1, 1, 1); PG8_SCHED; PG8_LDA(At, 1, 0); PG8_STAGE(PG8_SA(0, 1), a2 + hstep, voffA);
;             PG8_WAIT_V(8); PG8_WAIT_L(0); PG8_BAR; PG8_MMA(0, 0, At, B0); PG8_MMA(0, 1, At, B1); PG8_BAR; PG8_SCHED;
	s_setprio 1
	s_waitcnt lgkmcnt(0)
	v_mfma_f32_16x16x32_bf16 v[60:63], v[128:131], v[176:179], v[60:63]
	v_mfma_f32_16x16x32_bf16 v[56:59], v[146:149], v[176:179], v[56:59]
	v_mfma_f32_16x16x32_bf16 v[44:47], v[128:131], v[184:187], v[44:47]
	v_mfma_f32_16x16x32_bf16 v[40:43], v[146:149], v[184:187], v[40:43]
	v_mfma_f32_16x16x32_bf16 v[28:31], v[128:131], v[198:201], v[28:31]
	v_mfma_f32_16x16x32_bf16 v[24:27], v[146:149], v[198:201], v[24:27]
	v_mfma_f32_16x16x32_bf16 v[12:15], v[128:131], v[206:209], v[12:15]
	v_mfma_f32_16x16x32_bf16 v[8:11], v[146:149], v[206:209], v[8:11]
	v_mfma_f32_16x16x32_bf16 v[60:63], v[132:135], v[180:183], v[60:63]
	v_mfma_f32_16x16x32_bf16 v[56:59], v[150:153], v[180:183], v[56:59]
	v_mfma_f32_16x16x32_bf16 v[44:47], v[132:135], v[188:191], v[44:47]
	v_mfma_f32_16x16x32_bf16 v[40:43], v[150:153], v[188:191], v[40:43]
	v_mfma_f32_16x16x32_bf16 v[28:31], v[132:135], v[202:205], v[28:31]
	v_mfma_f32_16x16x32_bf16 v[24:27], v[150:153], v[202:205], v[24:27]
	v_mfma_f32_16x16x32_bf16 v[12:15], v[132:135], v[210:213], v[12:15]
	v_mfma_f32_16x16x32_bf16 v[8:11], v[150:153], v[210:213], v[8:11]
	s_setprio 0
	s_setprio 1
	v_mfma_f32_16x16x32_bf16 v[52:55], v[160:163], v[176:179], v[52:55]
	v_mfma_f32_16x16x32_bf16 v[48:51], v[168:171], v[176:179], v[48:51]
	v_mfma_f32_16x16x32_bf16 v[36:39], v[160:163], v[184:187], v[36:39]
	v_mfma_f32_16x16x32_bf16 v[32:35], v[168:171], v[184:187], v[32:35]
	v_mfma_f32_16x16x32_bf16 v[20:23], v[160:163], v[198:201], v[20:23]
	v_mfma_f32_16x16x32_bf16 v[16:19], v[168:171], v[198:201], v[16:19]
	v_mfma_f32_16x16x32_bf16 v[4:7], v[160:163], v[206:209], v[4:7]
	v_mfma_f32_16x16x32_bf16 v[0:3], v[168:171], v[206:209], v[0:3]
	v_mfma_f32_16x16x32_bf16 v[52:55], v[164:167], v[180:183], v[52:55]
	v_mfma_f32_16x16x32_bf16 v[48:51], v[172:175], v[180:183], v[48:51]
	v_mfma_f32_16x16x32_bf16 v[36:39], v[164:167], v[188:191], v[36:39]
	v_mfma_f32_16x16x32_bf16 v[32:35], v[172:175], v[188:191], v[32:35]
	v_mfma_f32_16x16x32_bf16 v[20:23], v[164:167], v[202:205], v[20:23]
	v_mfma_f32_16x16x32_bf16 v[16:19], v[172:175], v[202:205], v[16:19]
	v_mfma_f32_16x16x32_bf16 v[4:7], v[164:167], v[210:213], v[4:7]
	v_mfma_f32_16x16x32_bf16 v[0:3], v[172:175], v[210:213], v[0:3]
	s_setprio 0
	s_barrier
	v_add_u32_e32 v150, s91, v157
	v_add_u32_e32 v172, s58, v157
	ds_read_b128 v[128:131], v150
	ds_read_b128 v[132:135], v150 offset:1024
	ds_read_b128 v[146:149], v150 offset:2048
	ds_read_b128 v[150:153], v150 offset:3072
	ds_read_b128 v[160:163], v172
	ds_read_b128 v[164:167], v172 offset:1024
	ds_read_b128 v[168:171], v172 offset:2048
	ds_read_b128 v[172:175], v172 offset:3072
	ds_read_b128 v[176:179], v159 offset:32768
	ds_read_b128 v[180:183], v159 offset:33792
	ds_read_b128 v[184:187], v159 offset:34816
	ds_read_b128 v[188:191], v159 offset:35840
	ds_read_b128 v[198:201], v159 offset:36864
	ds_read_b128 v[202:205], v159 offset:37888
	ds_read_b128 v[206:209], v159 offset:38912
	ds_read_b128 v[210:213], v159 offset:39936
	s_mov_b32 m0, s3
	s_nop 0
	global_load_lds_dwordx4 v140, s[36:37]
	s_mov_b32 m0, s17
	s_nop 0
	global_load_lds_dwordx4 v138, s[36:37]
	s_add_u32 s36, s36, 0x100000
	s_addc_u32 s37, s37, 0
	s_mov_b32 m0, s38
	s_nop 0
	global_load_lds_dwordx4 v140, s[36:37]
	s_mov_b32 m0, s39
	s_nop 0
	global_load_lds_dwordx4 v138, s[36:37]
	s_waitcnt vmcnt(8)
	s_waitcnt lgkmcnt(0)
	s_barrier
; #define PG8_STAGE(bufoff, gbase, voff) do { _Pragma("unroll") for (int _i = 0; _i < 2; ++_i) \
;         __builtin_amdgcn_global_load_lds((const unsigned*)((const char*)(gbase) + (voff)[_i]), (LAS unsigned*)(lds + (bufoff) + ldsw + _i * 8192), 16, 0, 0); } while (0)
; #define PG8_LDA(dst, b, h) do { _Pragma("unroll") for (int m = 0; m < 4; ++m) _Pragma("unroll") for (int k = 0; k < 2; ++k) dst[m][k] = *(const LAS bf16x8*)(lds + PG8_SA(b, h) + aoff + m * 2048 + k * 1024); } while (0)
; #define PG8_MMA(ai, bj, At, Bt) do { __builtin_amdgcn_s_setprio(1); _Pragma("unroll") for (int m = 0; m < 4; ++m) _Pragma("unroll") for (int n = 0; n < 2; ++n) _Pragma("unroll") for (int k = 0; k < 2; ++k) \
;         acc[ai][bj][m][n] = __builtin_amdgcn_mfma_f32_16x16x32_bf16(Bt[n][k], At[m][k], acc[ai][bj][m][n], 0, 0, 0); __builtin_amdgcn_s_setprio(0); } while (0)
; #define PG8_WAIT_V(n) asm volatile("s_waitcnt vmcnt(" #n ")" ::: "memory")
; #define PG8_WAIT_L(n) asm volatile("s_waitcnt lgkmcnt(" #n ")" ::: "memory")
; #define PG8_BAR __builtin_amdgcn_s_barrier()
; #define PG8_SCHED __builtin_amdgcn_sched_barrier(0)
; template <class Epi, class Sched, bool ALIGN_EPI = false, bool SP2 = false>
; __device__ __forceinline__ void gemm_phase(LAS unsigned char* lds, const Gemm g, const Sched& S, const Epi& E) {
;     ...
;             PG8_WAIT_V(8); PG8_WAIT_L(0); PG8_BAR; PG8_MMA(0, 0, At, B0); PG8_MMA(0, 1, At, B1); PG8_BAR; PG8_SCHED;
;             PG8_LDA(At, 1, 1); PG8_STAGE(PG8_SB(1, 0), b3, voffB); PG8_STAGE(PG8_SB(1, 1), b3 + hstep, voffB); PG8_STAGE(PG8_SA(1, 0), a3, voffA);
;             PG8_WAIT_V(8); PG8_WAIT_L(0); PG8_BAR; PG8_MMA(1, 0, At, B0); PG8_MMA(1, 1, At, B1); PG8_BAR; PG8_SCHED;
;     ...
;         if constexpr (ALIGN_EPI) { if (wr == 0) PG8_BAR; }
	s_setprio 1
	s_waitcnt lgkmcnt(0)
	v_mfma_f32_16x16x32_bf16 v[124:127], v[128:131], v[176:179], v[124:127]
	v_mfma_f32_16x16x32_bf16 v[120:123], v[146:149], v[176:179], v[120:123]
	v_mfma_f32_16x16x32_bf16 v[108:111], v[128:131], v[184:187], v[108:111]
	v_mfma_f32_16x16x32_bf16 v[104:107], v[146:149], v[184:187], v[104:107]
	v_mfma_f32_16x16x32_bf16 v[92:95], v[128:131], v[198:201], v[92:95]
	v_mfma_f32_16x16x32_bf16 v[88:91], v[146:149], v[198:201], v[88:91]
	v_mfma_f32_16x16x32_bf16 v[76:79], v[128:131], v[206:209], v[76:79]
	v_mfma_f32_16x16x32_bf16 v[72:75], v[146:149], v[206:209], v[72:75]
	v_mfma_f32_16x16x32_bf16 v[124:127], v[132:135], v[180:183], v[124:127]
	v_mfma_f32_16x16x32_bf16 v[120:123], v[150:153], v[180:183], v[120:123]
	v_mfma_f32_16x16x32_bf16 v[108:111], v[132:135], v[188:191], v[108:111]
	v_mfma_f32_16x16x32_bf16 v[104:107], v[150:153], v[188:191], v[104:107]
	v_mfma_f32_16x16x32_bf16 v[92:95], v[132:135], v[202:205], v[92:95]
	v_mfma_f32_16x16x32_bf16 v[88:91], v[150:153], v[202:205], v[88:91]
	v_mfma_f32_16x16x32_bf16 v[76:79], v[132:135], v[210:213], v[76:79]
	v_mfma_f32_16x16x32_bf16 v[72:75], v[150:153], v[210:213], v[72:75]
	s_setprio 0
	s_setprio 1
	v_mfma_f32_16x16x32_bf16 v[116:119], v[160:163], v[176:179], v[116:119]
	v_mfma_f32_16x16x32_bf16 v[112:115], v[168:171], v[176:179], v[112:115]
	v_mfma_f32_16x16x32_bf16 v[100:103], v[160:163], v[184:187], v[100:103]
	v_mfma_f32_16x16x32_bf16 v[96:99], v[168:171], v[184:187], v[96:99]
	v_mfma_f32_16x16x32_bf16 v[84:87], v[160:163], v[198:201], v[84:87]
	v_mfma_f32_16x16x32_bf16 v[80:83], v[168:171], v[198:201], v[80:83]
	v_mfma_f32_16x16x32_bf16 v[68:71], v[160:163], v[206:209], v[68:71]
	v_mfma_f32_16x16x32_bf16 v[64:67], v[168:171], v[206:209], v[64:67]
	v_mfma_f32_16x16x32_bf16 v[116:119], v[164:167], v[180:183], v[116:119]
	v_mfma_f32_16x16x32_bf16 v[112:115], v[172:175], v[180:183], v[112:115]
	v_mfma_f32_16x16x32_bf16 v[100:103], v[164:167], v[188:191], v[100:103]
	v_mfma_f32_16x16x32_bf16 v[96:99], v[172:175], v[188:191], v[96:99]
	v_mfma_f32_16x16x32_bf16 v[84:87], v[164:167], v[202:205], v[84:87]
	v_mfma_f32_16x16x32_bf16 v[80:83], v[172:175], v[202:205], v[80:83]
	v_mfma_f32_16x16x32_bf16 v[68:71], v[164:167], v[210:213], v[68:71]
	v_mfma_f32_16x16x32_bf16 v[64:67], v[172:175], v[210:213], v[64:67]
	s_setprio 0
	s_barrier
	ds_read_b128 v[176:179], v159 offset:49152
	ds_read_b128 v[180:183], v159 offset:50176
	ds_read_b128 v[184:187], v159 offset:51200
	ds_read_b128 v[188:191], v159 offset:52224
	ds_read_b128 v[198:201], v159 offset:53248
	ds_read_b128 v[202:205], v159 offset:54272
	ds_read_b128 v[206:209], v159 offset:55296
	ds_read_b128 v[210:213], v159 offset:56320
	s_add_i32 s36, s91, s0
	s_mov_b32 m0, s36
	s_nop 0
	global_load_lds_dwordx4 v196, s[98:99]
	s_add_i32 m0, s36, 0x2000
	s_add_u32 s34, s34, 0x100080
	s_addc_u32 s35, s35, 0
	s_add_i32 s36, s58, s0
	global_load_lds_dwordx4 v136, s[98:99]
	s_mov_b32 m0, s36
	s_nop 0
	global_load_lds_dwordx4 v196, s[34:35]
	s_add_i32 m0, s36, 0x2000
	s_nop 0
	global_load_lds_dwordx4 v136, s[34:35]
	s_waitcnt vmcnt(6)
	s_waitcnt lgkmcnt(0)
	s_barrier
	s_setprio 1
	s_waitcnt lgkmcnt(0)
	v_mfma_f32_16x16x32_bf16 v[60:63], v[128:131], v[176:179], v[60:63]
	v_mfma_f32_16x16x32_bf16 v[56:59], v[146:149], v[176:179], v[56:59]
	v_mfma_f32_16x16x32_bf16 v[44:47], v[128:131], v[184:187], v[44:47]
	v_mfma_f32_16x16x32_bf16 v[40:43], v[146:149], v[184:187], v[40:43]
	v_mfma_f32_16x16x32_bf16 v[28:31], v[128:131], v[198:201], v[28:31]
	v_mfma_f32_16x16x32_bf16 v[24:27], v[146:149], v[198:201], v[24:27]
	v_mfma_f32_16x16x32_bf16 v[12:15], v[128:131], v[206:209], v[12:15]
	v_mfma_f32_16x16x32_bf16 v[8:11], v[146:149], v[206:209], v[8:11]
	v_mfma_f32_16x16x32_bf16 v[60:63], v[132:135], v[180:183], v[60:63]
	v_mfma_f32_16x16x32_bf16 v[56:59], v[150:153], v[180:183], v[56:59]
	v_mfma_f32_16x16x32_bf16 v[44:47], v[132:135], v[188:191], v[44:47]
	v_mfma_f32_16x16x32_bf16 v[40:43], v[150:153], v[188:191], v[40:43]
	v_mfma_f32_16x16x32_bf16 v[28:31], v[132:135], v[202:205], v[28:31]
	v_mfma_f32_16x16x32_bf16 v[24:27], v[150:153], v[202:205], v[24:27]
	v_mfma_f32_16x16x32_bf16 v[12:15], v[132:135], v[210:213], v[12:15]
	v_mfma_f32_16x16x32_bf16 v[8:11], v[150:153], v[210:213], v[8:11]
	s_setprio 0
	s_setprio 1
	v_mfma_f32_16x16x32_bf16 v[52:55], v[160:163], v[176:179], v[52:55]
	v_mfma_f32_16x16x32_bf16 v[48:51], v[168:171], v[176:179], v[48:51]
	v_mfma_f32_16x16x32_bf16 v[36:39], v[160:163], v[184:187], v[36:39]
	v_mfma_f32_16x16x32_bf16 v[32:35], v[168:171], v[184:187], v[32:35]
	v_mfma_f32_16x16x32_bf16 v[20:23], v[160:163], v[198:201], v[20:23]
	v_mfma_f32_16x16x32_bf16 v[16:19], v[168:171], v[198:201], v[16:19]
	v_mfma_f32_16x16x32_bf16 v[4:7], v[160:163], v[206:209], v[4:7]
	v_mfma_f32_16x16x32_bf16 v[0:3], v[168:171], v[206:209], v[0:3]
	v_mfma_f32_16x16x32_bf16 v[52:55], v[164:167], v[180:183], v[52:55]
	v_mfma_f32_16x16x32_bf16 v[48:51], v[172:175], v[180:183], v[48:51]
	v_mfma_f32_16x16x32_bf16 v[36:39], v[164:167], v[188:191], v[36:39]
	v_mfma_f32_16x16x32_bf16 v[32:35], v[172:175], v[188:191], v[32:35]
	v_mfma_f32_16x16x32_bf16 v[20:23], v[164:167], v[202:205], v[20:23]
	v_mfma_f32_16x16x32_bf16 v[16:19], v[172:175], v[202:205], v[16:19]
	v_mfma_f32_16x16x32_bf16 v[4:7], v[164:167], v[210:213], v[4:7]
	v_mfma_f32_16x16x32_bf16 v[0:3], v[172:175], v[210:213], v[0:3]
	s_setprio 0
	s_barrier
	s_add_i32 s62, s62, 2
	s_add_u32 s10, s10, 0x100
	s_addc_u32 s11, s11, 0
	s_add_u32 s54, s54, 0x100
	s_addc_u32 s59, s59, 0
	s_cmp_gt_u32 s62, 61
	s_cbranch_scc0 .LBB0_832
	s_and_b64 vcc, exec, s[20:21]
	s_cbranch_vccz .LBB0_835
	s_barrier
